# hand-scheduled cross-attention unit (LDS fragment reads issued 5 MFMAs ahead with counted lgkmcnt, packed softmax math), replaces the compiled unit when grid is 256
# speedup vs baseline: 1.0076x; 1.0074x over previous
.LBB0_266:
	s_and_b64 vcc, exec, s[12:13]
	s_cbranch_vccz .LBB0_293
	v_readlane_b32 s10, v253, 7
	v_mov_b32_e32 v76, v241
	v_readlane_b32 s11, v253, 8
	s_and_b64 vcc, exec, s[10:11]
	v_readfirstlane_b32 s6, v76
	s_cbranch_vccz .LBB0_270
	s_and_b64 s[8:9], s[8:9], exec
	s_movk_i32 s8, 0x700
	s_cselect_b32 s10, s8, 0x400
	s_movk_i32 s8, 0xc00
	s_cselect_b32 s8, s8, 0x600
	s_add_u32 s8, s72, s8
	v_readlane_b32 s12, v254, 58
	s_addc_u32 s9, s73, 0
	v_readlane_b32 s13, v254, 59
	s_and_b64 s[12:13], s[12:13], exec
	s_cselect_b32 s11, 0x80000, 0
	v_readlane_b32 s12, v252, 53
	s_add_u32 s12, s12, s11
	v_readlane_b32 s13, v252, 54
	s_addc_u32 s13, s13, 0
	v_readlane_b32 s14, v252, 55
	s_add_u32 s14, s14, s11
	v_readlane_b32 s11, v252, 56
	v_lshlrev_b32_e32 v2, 4, v76
	s_addc_u32 s15, s11, 0
	v_and_b32_e32 v0, 0x70, v2
	v_mov_b32_e32 v1, v185
	v_lshl_add_u64 v[64:65], s[14:15], 0, v[0:1]
	v_add_u32_e32 v1, 0x200, v76
	v_ashrrev_i32_e32 v79, 3, v1
	v_ashrrev_i32_e32 v80, 5, v1
	v_add_u32_e32 v1, 0x400, v76
	v_ashrrev_i32_e32 v81, 3, v1
	v_ashrrev_i32_e32 v82, 5, v1
	v_add_u32_e32 v1, 0x600, v76
	v_and_b32_e32 v15, 64, v243
	v_ashrrev_i32_e32 v83, 3, v1
	v_ashrrev_i32_e32 v84, 5, v1
	v_add_u32_e32 v1, 0, v0
	v_xor_b32_e32 v0, 16, v243
	v_add_u32_e32 v15, 64, v15
	v_cmp_lt_i32_e32 vcc, v0, v15
	s_ashr_i32 s6, s6, 1
	v_and_b32_e32 v4, 63, v76
	v_cndmask_b32_e32 v0, v243, v0, vcc
	v_lshlrev_b32_e32 v85, 2, v0
	v_xor_b32_e32 v0, 32, v243
	v_and_b32_e32 v5, 15, v76
	s_andn2_b32 s6, s6, 31
	v_and_b32_e32 v184, 48, v76
	v_cmp_lt_i32_e32 vcc, v0, v15
	v_bfe_u32 v6, v76, 4, 2
	s_ashr_i32 s11, s6, 31
	v_or_b32_e32 v60, s6, v5
	v_lshl_add_u64 v[62:63], s[8:9], 0, v[184:185]
	v_and_b32_e32 v2, 0x1f0, v2
	v_mov_b32_e32 v3, v185
	v_ashrrev_i32_e32 v77, 3, v76
	v_ashrrev_i32_e32 v78, 5, v76
	s_movk_i32 s6, 0x90
	s_movk_i32 s8, 0x210
	v_cndmask_b32_e32 v0, v243, v0, vcc
	v_or_b32_e32 v16, 48, v4
	v_or_b32_e32 v18, 0x70, v4
	v_or_b32_e32 v19, 0xb0, v4
	v_or_b32_e32 v4, 0xf0, v4
	v_lshl_add_u64 v[66:67], s[12:13], 0, v[2:3]
	v_add_u32_e32 v2, 0, v2
	v_mul_lo_u32 v3, v77, s6
	v_mul_lo_u32 v7, v78, s8
	v_mul_lo_u32 v8, v79, s6
	v_mul_lo_u32 v9, v80, s8
	v_mul_lo_u32 v10, v81, s6
	v_mul_lo_u32 v11, v82, s8
	v_mul_lo_u32 v12, v83, s6
	v_mul_lo_u32 v13, v84, s8
	v_add_u32_e32 v14, 0, v184
	v_lshlrev_b32_e32 v86, 2, v0
	v_lshl_add_u32 v15, v6, 3, 0
	v_lshlrev_b32_e32 v0, 2, v6
	v_mul_u32_u24_e32 v6, 0x90, v5
	v_mul_u32_u24_e32 v17, 0x90, v16
	v_mul_u32_u24_e32 v18, 0x90, v18
	v_mul_u32_u24_e32 v19, 0x90, v19
	v_mul_u32_u24_e32 v4, 0x90, v4
	v_mul_u32_u24_e32 v5, 0x210, v5
	v_mul_u32_u24_e32 v16, 0x210, v16
	v_mov_b32_e32 v61, s11
	v_add_u32_e32 v87, v1, v3
	v_add_u32_e32 v88, v2, v7
	v_add_u32_e32 v89, v1, v8
	v_add_u32_e32 v90, v2, v9
	v_add_u32_e32 v91, v1, v10
	v_add_u32_e32 v92, v2, v11
	v_add_u32_e32 v93, v1, v12
	v_add_u32_e32 v94, v2, v13
	v_add_u32_e32 v95, v14, v6
	v_add_u32_e32 v96, v14, v17
	v_add_u32_e32 v97, v14, v18
	v_add_u32_e32 v98, v14, v19
	v_add_u32_e32 v99, v14, v4
	v_add_u32_e32 v100, v15, v5
	v_add_u32_e32 v101, v15, v16
	v_lshlrev_b32_e32 v184, 1, v0
	v_readlane_b32 s11, v252, 33
	s_mov_b32 s12, s87
	s_cmp_eq_u32 s100, 1
	s_cbranch_scc0 .Latt_nomap
	v_readlane_b32 s6, v252, 0
	s_nop 0
	s_and_b32 s8, s6, 7
	s_lshr_b32 s6, s6, 3
	s_lshr_b32 s13, s8, 1
	s_lshl_b32 s13, s13, 2
	s_lshr_b32 s14, s6, 3
	s_add_i32 s13, s13, s14
	s_lshl_b32 s13, s13, 4
	s_and_b32 s14, s8, 1
	s_lshl_b32 s14, s14, 3
	s_and_b32 s6, s6, 7
	s_add_i32 s14, s14, s6
	s_add_i32 s12, s13, s14
	s_lshl_b32 s11, s12, 9
	s_lshr_b32 s6, s12, 6
	s_bfe_u32 s8, s12, 0x20004
	s_and_b32 s9, s12, 15
	s_lshl_b32 s13, s6, 13
	s_lshl_b32 s14, s9, 9
	s_add_i32 s13, s13, s14
	v_readlane_b32 s14, v254, 58
	v_readlane_b32 s16, v252, 45
	v_readlane_b32 s17, v252, 46
	s_lshl_b32 s70, s8, 7
	s_cmp_lg_u32 s14, 0
	s_cselect_b32 s11, 1, 0
	v_and_b32_e32 v32, 63, v241
	v_and_b32_e32 v33, 15, v32
	v_lshrrev_b32_e32 v34, 4, v32
	v_lshrrev_b32_e32 v35, 6, v241
	v_lshl_add_u32 v36, v35, 5, v33
	v_mul_u32_u24_e32 v72, 0x90, v33
	v_lshl_add_u32 v72, v34, 4, v72
	v_mul_u32_u24_e32 v73, 0x210, v33
	v_lshl_add_u32 v73, v34, 3, v73
	v_xor_b32_e32 v75, 16, v32
	v_lshlrev_b32_e32 v75, 2, v75
	v_xor_b32_e32 v77, 32, v32
	v_lshlrev_b32_e32 v77, 2, v77
	v_lshlrev_b32_e32 v74, 11, v36
	v_lshl_add_u32 v74, v34, 3, v74
	v_mov_b32_e32 v144, 0x3e38aa3b
	v_mov_b32_e32 v145, 0x3e38aa3b
	v_lshrrev_b32_e32 v38, 3, v241
	v_and_b32_e32 v39, 7, v241
	v_lshlrev_b32_e32 v40, 9, v38
	v_lshl_add_u32 v40, v39, 4, v40
	v_mul_u32_u24_e32 v41, 0x90, v38
	v_lshl_add_u32 v41, v39, 4, v41
	v_lshrrev_b32_e32 v38, 5, v241
	v_and_b32_e32 v39, 31, v241
	v_lshlrev_b32_e32 v42, 11, v38
	v_lshl_add_u32 v42, v39, 4, v42
	v_mul_u32_u24_e32 v43, 0x210, v38
	v_lshl_add_u32 v43, v39, 4, v43
	s_lshl_b32 s14, s11, 19
	s_add_i32 s14, s14, 0x100000
	s_lshl_b32 s15, s6, 17
	s_add_i32 s14, s14, s15
	s_add_i32 s14, s14, s70
	s_add_u32 s14, s16, s14
	s_addc_u32 s15, s17, 0
	s_lshl_b32 s8, s11, 19
	s_add_i32 s8, s8, 0x200000
	s_lshl_b32 s9, s70, 10
	s_add_i32 s8, s8, s9
	s_lshl_b32 s9, s6, 9
	s_add_i32 s8, s8, s9
	s_add_u32 s8, s16, s8
	s_addc_u32 s9, s17, 0
	global_load_dwordx4 v[78:81], v40, s[14:15]
	global_load_dwordx4 v[94:97], v42, s[8:9]
	s_add_u32 s14, s14, 0x8000
	s_addc_u32 s15, s15, 0
	s_add_u32 s8, s8, 0x8000
	s_addc_u32 s9, s9, 0
	global_load_dwordx4 v[82:85], v40, s[14:15]
	global_load_dwordx4 v[98:101], v42, s[8:9]
	s_add_u32 s14, s14, 0x8000
	s_addc_u32 s15, s15, 0
	s_add_u32 s8, s8, 0x8000
	s_addc_u32 s9, s9, 0
	global_load_dwordx4 v[86:89], v40, s[14:15]
	global_load_dwordx4 v[102:105], v42, s[8:9]
	s_add_u32 s14, s14, 0x8000
	s_addc_u32 s15, s15, 0
	s_add_u32 s8, s8, 0x8000
	s_addc_u32 s9, s9, 0
	global_load_dwordx4 v[90:93], v40, s[14:15]
	global_load_dwordx4 v[106:109], v42, s[8:9]
	s_cmp_eq_u32 s11, 1
	s_movk_i32 s6, 0xe00
	s_cselect_b32 s6, 0x800, s6
	s_movk_i32 s14, 0xc00
	s_cselect_b32 s14, 0x600, s14
	s_mul_i32 s12, s13, s6
	s_add_i32 s12, s12, s14
	s_add_i32 s12, s12, s70
	s_add_u32 s12, s12, 0xd800000
	s_add_u32 s8, s16, s12
	s_addc_u32 s9, s17, 0
	v_mul_lo_u32 v37, v36, s6
	v_lshl_add_u32 v37, v34, 4, v37
	s_mul_i32 s12, s6, 0
	s_add_u32 s14, s8, s12
	s_addc_u32 s15, s9, 0
	global_load_dwordx4 v[0:3], v37, s[14:15]
	global_load_dwordx4 v[4:7], v37, s[14:15] offset:64
	s_mul_i32 s12, s6, 16
	s_add_u32 s14, s8, s12
	s_addc_u32 s15, s9, 0
	global_load_dwordx4 v[8:11], v37, s[14:15]
	global_load_dwordx4 v[12:15], v37, s[14:15] offset:64
	s_mul_i32 s12, s6, 256
	s_add_u32 s14, s8, s12
	s_addc_u32 s15, s9, 0
	global_load_dwordx4 v[16:19], v37, s[14:15]
	global_load_dwordx4 v[20:23], v37, s[14:15] offset:64
	s_mul_i32 s12, s6, 272
	s_add_u32 s14, s8, s12
	s_addc_u32 s15, s9, 0
	global_load_dwordx4 v[24:27], v37, s[14:15]
	global_load_dwordx4 v[28:31], v37, s[14:15] offset:64
	s_lshl_b32 s12, s13, 11
	s_add_i32 s12, s12, s70
	s_add_u32 s12, s12, 0x9800600
	s_add_u32 s12, s16, s12
	s_addc_u32 s13, s17, 0
	s_waitcnt vmcnt(8)
	ds_write_b128 v41, v[78:81] offset:0
	ds_write_b128 v43, v[94:97] offset:36864
	ds_write_b128 v41, v[82:85] offset:9216
	ds_write_b128 v43, v[98:101] offset:45312
	ds_write_b128 v41, v[86:89] offset:18432
	ds_write_b128 v43, v[102:105] offset:53760
	ds_write_b128 v41, v[90:93] offset:27648
	ds_write_b128 v43, v[106:109] offset:62208
	s_waitcnt vmcnt(0) lgkmcnt(0)
	s_barrier
	ds_read_b128 v[48:51], v72 offset:0
	ds_read_b128 v[52:55], v72 offset:64
	ds_read_b128 v[56:59], v72 offset:2304
	ds_read_b128 v[60:63], v72 offset:2368
	ds_read_b128 v[64:67], v72 offset:4608
	ds_read_b128 v[68:71], v72 offset:4672
	s_waitcnt lgkmcnt(5)
	v_mfma_f32_16x16x32_bf16 v[78:81], v[48:51], v[0:3], 0
	ds_read_b128 v[48:51], v72 offset:6912
	s_waitcnt lgkmcnt(5)
	v_mfma_f32_16x16x32_bf16 v[78:81], v[52:55], v[4:7], v[78:81]
	ds_read_b128 v[52:55], v72 offset:6976
	s_waitcnt lgkmcnt(5)
	v_mfma_f32_16x16x32_bf16 v[82:85], v[56:59], v[0:3], 0
	ds_read_b128 v[56:59], v72 offset:9216
	s_waitcnt lgkmcnt(5)
	v_mfma_f32_16x16x32_bf16 v[82:85], v[60:63], v[4:7], v[82:85]
	ds_read_b128 v[60:63], v72 offset:9280
	s_waitcnt lgkmcnt(5)
	v_mfma_f32_16x16x32_bf16 v[86:89], v[64:67], v[0:3], 0
	ds_read_b128 v[64:67], v72 offset:11520
	s_waitcnt lgkmcnt(5)
	v_mfma_f32_16x16x32_bf16 v[86:89], v[68:71], v[4:7], v[86:89]
	ds_read_b128 v[68:71], v72 offset:11584
	s_waitcnt lgkmcnt(5)
	v_mfma_f32_16x16x32_bf16 v[90:93], v[48:51], v[0:3], 0
	ds_read_b128 v[48:51], v72 offset:13824
	s_waitcnt lgkmcnt(5)
	v_mfma_f32_16x16x32_bf16 v[90:93], v[52:55], v[4:7], v[90:93]
	ds_read_b128 v[52:55], v72 offset:13888
	s_waitcnt lgkmcnt(5)
	v_mfma_f32_16x16x32_bf16 v[94:97], v[56:59], v[0:3], 0
	ds_read_b128 v[56:59], v72 offset:16128
	s_waitcnt lgkmcnt(5)
	v_mfma_f32_16x16x32_bf16 v[94:97], v[60:63], v[4:7], v[94:97]
	ds_read_b128 v[60:63], v72 offset:16192
	s_waitcnt lgkmcnt(5)
	v_mfma_f32_16x16x32_bf16 v[98:101], v[64:67], v[0:3], 0
	ds_read_b128 v[64:67], v72 offset:18432
	s_waitcnt lgkmcnt(5)
	v_mfma_f32_16x16x32_bf16 v[98:101], v[68:71], v[4:7], v[98:101]
	ds_read_b128 v[68:71], v72 offset:18496
	s_waitcnt lgkmcnt(5)
	v_mfma_f32_16x16x32_bf16 v[102:105], v[48:51], v[0:3], 0
	ds_read_b128 v[48:51], v72 offset:20736
	s_waitcnt lgkmcnt(5)
	v_mfma_f32_16x16x32_bf16 v[102:105], v[52:55], v[4:7], v[102:105]
	ds_read_b128 v[52:55], v72 offset:20800
	s_waitcnt lgkmcnt(5)
	v_mfma_f32_16x16x32_bf16 v[106:109], v[56:59], v[0:3], 0
	ds_read_b128 v[56:59], v72 offset:23040
	s_waitcnt lgkmcnt(5)
	v_mfma_f32_16x16x32_bf16 v[106:109], v[60:63], v[4:7], v[106:109]
	ds_read_b128 v[60:63], v72 offset:23104
	s_waitcnt lgkmcnt(5)
	v_mfma_f32_16x16x32_bf16 v[110:113], v[64:67], v[0:3], 0
	ds_read_b128 v[64:67], v72 offset:25344
	s_waitcnt lgkmcnt(5)
	v_mfma_f32_16x16x32_bf16 v[110:113], v[68:71], v[4:7], v[110:113]
	ds_read_b128 v[68:71], v72 offset:25408
	s_waitcnt lgkmcnt(5)
	v_mfma_f32_16x16x32_bf16 v[114:117], v[48:51], v[0:3], 0
	ds_read_b128 v[48:51], v72 offset:27648
	s_waitcnt lgkmcnt(5)
	v_mfma_f32_16x16x32_bf16 v[114:117], v[52:55], v[4:7], v[114:117]
	ds_read_b128 v[52:55], v72 offset:27712
	s_waitcnt lgkmcnt(5)
	v_mfma_f32_16x16x32_bf16 v[118:121], v[56:59], v[0:3], 0
	ds_read_b128 v[56:59], v72 offset:29952
	s_waitcnt lgkmcnt(5)
	v_mfma_f32_16x16x32_bf16 v[118:121], v[60:63], v[4:7], v[118:121]
	ds_read_b128 v[60:63], v72 offset:30016
	s_waitcnt lgkmcnt(5)
	v_mfma_f32_16x16x32_bf16 v[122:125], v[64:67], v[0:3], 0
	ds_read_b128 v[64:67], v72 offset:32256
	s_waitcnt lgkmcnt(5)
	v_mfma_f32_16x16x32_bf16 v[122:125], v[68:71], v[4:7], v[122:125]
	ds_read_b128 v[68:71], v72 offset:32320
	s_waitcnt lgkmcnt(5)
	v_mfma_f32_16x16x32_bf16 v[126:129], v[48:51], v[0:3], 0
	ds_read_b128 v[48:51], v72 offset:34560
	s_waitcnt lgkmcnt(5)
	v_mfma_f32_16x16x32_bf16 v[126:129], v[52:55], v[4:7], v[126:129]
	ds_read_b128 v[52:55], v72 offset:34624
	s_waitcnt lgkmcnt(5)
	v_mfma_f32_16x16x32_bf16 v[130:133], v[56:59], v[0:3], 0
	s_waitcnt lgkmcnt(4)
	v_mfma_f32_16x16x32_bf16 v[130:133], v[60:63], v[4:7], v[130:133]
	s_waitcnt lgkmcnt(3)
	v_mfma_f32_16x16x32_bf16 v[134:137], v[64:67], v[0:3], 0
	s_waitcnt lgkmcnt(2)
	v_mfma_f32_16x16x32_bf16 v[134:137], v[68:71], v[4:7], v[134:137]
	s_waitcnt lgkmcnt(1)
	v_mfma_f32_16x16x32_bf16 v[138:141], v[48:51], v[0:3], 0
	s_waitcnt lgkmcnt(0)
	v_mfma_f32_16x16x32_bf16 v[138:141], v[52:55], v[4:7], v[138:141]
	v_max3_f32 v36, v78, v79, v80
	v_max3_f32 v36, v36, v81, v82
	v_max3_f32 v36, v36, v83, v84
	v_max3_f32 v36, v36, v85, v86
	v_max3_f32 v36, v36, v87, v88
	v_max3_f32 v36, v36, v89, v90
	v_max3_f32 v36, v36, v91, v92
	v_max3_f32 v36, v36, v93, v94
	v_max3_f32 v36, v36, v95, v96
	v_max3_f32 v36, v36, v97, v98
	v_max3_f32 v36, v36, v99, v100
	v_max3_f32 v36, v36, v101, v102
	v_max3_f32 v36, v36, v103, v104
	v_max3_f32 v36, v36, v105, v106
	v_max3_f32 v36, v36, v107, v108
	v_max3_f32 v36, v36, v109, v110
	v_max3_f32 v36, v36, v111, v112
	v_max3_f32 v36, v36, v113, v114
	v_max3_f32 v36, v36, v115, v116
	v_max3_f32 v36, v36, v117, v118
	v_max3_f32 v36, v36, v119, v120
	v_max3_f32 v36, v36, v121, v122
	v_max3_f32 v36, v36, v123, v124
	v_max3_f32 v36, v36, v125, v126
	v_max3_f32 v36, v36, v127, v128
	v_max3_f32 v36, v36, v129, v130
	v_max3_f32 v36, v36, v131, v132
	v_max3_f32 v36, v36, v133, v134
	v_max3_f32 v36, v36, v135, v136
	v_max3_f32 v36, v36, v137, v138
	v_max3_f32 v36, v36, v139, v140
	v_max_f32_e32 v36, v36, v141
	ds_bpermute_b32 v37, v75, v36
	s_waitcnt lgkmcnt(0)
	v_max_f32_e32 v36, v36, v37
	ds_bpermute_b32 v37, v77, v36
	s_waitcnt lgkmcnt(0)
	v_max_f32_e32 v36, v36, v37
	v_mul_f32_e64 v34, v36, -v144
	v_mov_b32_e32 v32, 0
	v_mov_b32_e32 v33, 0
	v_mov_b32_e32 v35, v34
	v_pk_fma_f32 v[78:79], v[78:79], v[144:145], v[34:35]
	v_pk_fma_f32 v[80:81], v[80:81], v[144:145], v[34:35]
	v_exp_f32_e32 v78, v78
	v_exp_f32_e32 v79, v79
	v_exp_f32_e32 v80, v80
	v_exp_f32_e32 v81, v81
	v_pk_fma_f32 v[82:83], v[82:83], v[144:145], v[34:35]
	v_pk_fma_f32 v[84:85], v[84:85], v[144:145], v[34:35]
	v_exp_f32_e32 v82, v82
	v_exp_f32_e32 v83, v83
	v_exp_f32_e32 v84, v84
	v_exp_f32_e32 v85, v85
	v_pk_add_f32 v[32:33], v[32:33], v[78:79]
	v_pk_add_f32 v[32:33], v[32:33], v[80:81]
	v_pk_fma_f32 v[86:87], v[86:87], v[144:145], v[34:35]
	v_pk_fma_f32 v[88:89], v[88:89], v[144:145], v[34:35]
	v_exp_f32_e32 v86, v86
	v_exp_f32_e32 v87, v87
	v_exp_f32_e32 v88, v88
	v_exp_f32_e32 v89, v89
	v_pk_add_f32 v[32:33], v[32:33], v[82:83]
	v_pk_add_f32 v[32:33], v[32:33], v[84:85]
	v_pk_fma_f32 v[90:91], v[90:91], v[144:145], v[34:35]
	v_pk_fma_f32 v[92:93], v[92:93], v[144:145], v[34:35]
	v_exp_f32_e32 v90, v90
	v_exp_f32_e32 v91, v91
	v_exp_f32_e32 v92, v92
	v_exp_f32_e32 v93, v93
	v_pk_add_f32 v[32:33], v[32:33], v[86:87]
	v_pk_add_f32 v[32:33], v[32:33], v[88:89]
	v_pk_fma_f32 v[94:95], v[94:95], v[144:145], v[34:35]
	v_pk_fma_f32 v[96:97], v[96:97], v[144:145], v[34:35]
	v_exp_f32_e32 v94, v94
	v_exp_f32_e32 v95, v95
	v_exp_f32_e32 v96, v96
	v_exp_f32_e32 v97, v97
	v_pk_add_f32 v[32:33], v[32:33], v[90:91]
	v_pk_add_f32 v[32:33], v[32:33], v[92:93]
	v_pk_fma_f32 v[98:99], v[98:99], v[144:145], v[34:35]
	v_pk_fma_f32 v[100:101], v[100:101], v[144:145], v[34:35]
	v_exp_f32_e32 v98, v98
	v_exp_f32_e32 v99, v99
	v_exp_f32_e32 v100, v100
	v_exp_f32_e32 v101, v101
	v_pk_add_f32 v[32:33], v[32:33], v[94:95]
	v_pk_add_f32 v[32:33], v[32:33], v[96:97]
	v_pk_fma_f32 v[102:103], v[102:103], v[144:145], v[34:35]
	v_pk_fma_f32 v[104:105], v[104:105], v[144:145], v[34:35]
	v_exp_f32_e32 v102, v102
	v_exp_f32_e32 v103, v103
	v_exp_f32_e32 v104, v104
	v_exp_f32_e32 v105, v105
	v_pk_add_f32 v[32:33], v[32:33], v[98:99]
	v_pk_add_f32 v[32:33], v[32:33], v[100:101]
	v_pk_fma_f32 v[106:107], v[106:107], v[144:145], v[34:35]
	v_pk_fma_f32 v[108:109], v[108:109], v[144:145], v[34:35]
	v_exp_f32_e32 v106, v106
	v_exp_f32_e32 v107, v107
	v_exp_f32_e32 v108, v108
	v_exp_f32_e32 v109, v109
	v_pk_add_f32 v[32:33], v[32:33], v[102:103]
	v_pk_add_f32 v[32:33], v[32:33], v[104:105]
	v_pk_fma_f32 v[110:111], v[110:111], v[144:145], v[34:35]
	v_pk_fma_f32 v[112:113], v[112:113], v[144:145], v[34:35]
	v_exp_f32_e32 v110, v110
	v_exp_f32_e32 v111, v111
	v_exp_f32_e32 v112, v112
	v_exp_f32_e32 v113, v113
	v_pk_add_f32 v[32:33], v[32:33], v[106:107]
	v_pk_add_f32 v[32:33], v[32:33], v[108:109]
	v_pk_fma_f32 v[114:115], v[114:115], v[144:145], v[34:35]
	v_pk_fma_f32 v[116:117], v[116:117], v[144:145], v[34:35]
	v_exp_f32_e32 v114, v114
	v_exp_f32_e32 v115, v115
	v_exp_f32_e32 v116, v116
	v_exp_f32_e32 v117, v117
	v_pk_add_f32 v[32:33], v[32:33], v[110:111]
	v_pk_add_f32 v[32:33], v[32:33], v[112:113]
	v_pk_fma_f32 v[118:119], v[118:119], v[144:145], v[34:35]
	v_pk_fma_f32 v[120:121], v[120:121], v[144:145], v[34:35]
	v_exp_f32_e32 v118, v118
	v_exp_f32_e32 v119, v119
	v_exp_f32_e32 v120, v120
	v_exp_f32_e32 v121, v121
	v_pk_add_f32 v[32:33], v[32:33], v[114:115]
	v_pk_add_f32 v[32:33], v[32:33], v[116:117]
	v_pk_fma_f32 v[122:123], v[122:123], v[144:145], v[34:35]
	v_pk_fma_f32 v[124:125], v[124:125], v[144:145], v[34:35]
	v_exp_f32_e32 v122, v122
	v_exp_f32_e32 v123, v123
	v_exp_f32_e32 v124, v124
	v_exp_f32_e32 v125, v125
	v_pk_add_f32 v[32:33], v[32:33], v[118:119]
	v_pk_add_f32 v[32:33], v[32:33], v[120:121]
	v_pk_fma_f32 v[126:127], v[126:127], v[144:145], v[34:35]
	v_pk_fma_f32 v[128:129], v[128:129], v[144:145], v[34:35]
	v_exp_f32_e32 v126, v126
	v_exp_f32_e32 v127, v127
	v_exp_f32_e32 v128, v128
	v_exp_f32_e32 v129, v129
	v_pk_add_f32 v[32:33], v[32:33], v[122:123]
	v_pk_add_f32 v[32:33], v[32:33], v[124:125]
	v_pk_fma_f32 v[130:131], v[130:131], v[144:145], v[34:35]
	v_pk_fma_f32 v[132:133], v[132:133], v[144:145], v[34:35]
	v_exp_f32_e32 v130, v130
	v_exp_f32_e32 v131, v131
	v_exp_f32_e32 v132, v132
	v_exp_f32_e32 v133, v133
	v_pk_add_f32 v[32:33], v[32:33], v[126:127]
	v_pk_add_f32 v[32:33], v[32:33], v[128:129]
	v_pk_fma_f32 v[134:135], v[134:135], v[144:145], v[34:35]
	v_pk_fma_f32 v[136:137], v[136:137], v[144:145], v[34:35]
	v_exp_f32_e32 v134, v134
	v_exp_f32_e32 v135, v135
	v_exp_f32_e32 v136, v136
	v_exp_f32_e32 v137, v137
	v_pk_add_f32 v[32:33], v[32:33], v[130:131]
	v_pk_add_f32 v[32:33], v[32:33], v[132:133]
	v_pk_fma_f32 v[138:139], v[138:139], v[144:145], v[34:35]
	v_pk_fma_f32 v[140:141], v[140:141], v[144:145], v[34:35]
	v_exp_f32_e32 v138, v138
	v_exp_f32_e32 v139, v139
	v_exp_f32_e32 v140, v140
	v_exp_f32_e32 v141, v141
	v_pk_add_f32 v[32:33], v[32:33], v[134:135]
	v_pk_add_f32 v[32:33], v[32:33], v[136:137]
	s_nop 0
	v_pk_add_f32 v[32:33], v[32:33], v[138:139]
	v_pk_add_f32 v[32:33], v[32:33], v[140:141]
	v_add_f32_e32 v36, v32, v33
	ds_bpermute_b32 v37, v75, v36
	v_cvt_pk_bf16_f32 v78, v78, v79
	v_cvt_pk_bf16_f32 v79, v80, v81
	v_cvt_pk_bf16_f32 v80, v82, v83
	v_cvt_pk_bf16_f32 v81, v84, v85
	v_cvt_pk_bf16_f32 v86, v86, v87
	v_cvt_pk_bf16_f32 v87, v88, v89
	v_cvt_pk_bf16_f32 v88, v90, v91
	v_cvt_pk_bf16_f32 v89, v92, v93
	v_cvt_pk_bf16_f32 v94, v94, v95
	v_cvt_pk_bf16_f32 v95, v96, v97
	v_cvt_pk_bf16_f32 v96, v98, v99
	v_cvt_pk_bf16_f32 v97, v100, v101
	v_cvt_pk_bf16_f32 v102, v102, v103
	v_cvt_pk_bf16_f32 v103, v104, v105
	v_cvt_pk_bf16_f32 v104, v106, v107
	v_cvt_pk_bf16_f32 v105, v108, v109
	v_cvt_pk_bf16_f32 v110, v110, v111
	v_cvt_pk_bf16_f32 v111, v112, v113
	v_cvt_pk_bf16_f32 v112, v114, v115
	v_cvt_pk_bf16_f32 v113, v116, v117
	v_cvt_pk_bf16_f32 v118, v118, v119
	v_cvt_pk_bf16_f32 v119, v120, v121
	v_cvt_pk_bf16_f32 v120, v122, v123
	v_cvt_pk_bf16_f32 v121, v124, v125
	v_cvt_pk_bf16_f32 v126, v126, v127
	v_cvt_pk_bf16_f32 v127, v128, v129
	v_cvt_pk_bf16_f32 v128, v130, v131
	v_cvt_pk_bf16_f32 v129, v132, v133
	v_cvt_pk_bf16_f32 v134, v134, v135
	v_cvt_pk_bf16_f32 v135, v136, v137
	v_cvt_pk_bf16_f32 v136, v138, v139
	v_cvt_pk_bf16_f32 v137, v140, v141
	s_waitcnt lgkmcnt(0)
	v_add_f32_e32 v36, v36, v37
	ds_bpermute_b32 v37, v77, v36
	ds_read_b64 v[48:49], v73 offset:36864
	ds_read_b64 v[50:51], v73 offset:36896
	ds_read_b64 v[52:53], v73 offset:45312
	ds_read_b64 v[54:55], v73 offset:45344
	ds_read_b64 v[56:57], v73 offset:53760
	ds_read_b64 v[58:59], v73 offset:53792
	ds_read_b64 v[60:61], v73 offset:62208
	ds_read_b64 v[62:63], v73 offset:62240
	ds_read_b64 v[64:65], v73 offset:36928
	ds_read_b64 v[66:67], v73 offset:36960
	s_waitcnt lgkmcnt(10)
	v_add_f32_e32 v36, v36, v37
	v_rcp_f32_e32 v142, v36
	s_nop 0
	v_fma_f32 v143, -v36, v142, 1.0
	v_fma_f32 v142, v143, v142, v142
	v_mov_b32_e32 v143, v142
	ds_read_b64 v[68:69], v73 offset:45376
	ds_read_b64 v[70:71], v73 offset:45408
	s_waitcnt lgkmcnt(10)
	v_mfma_f32_16x16x32_bf16 v[32:35], v[48:51], v[78:81], 0
	ds_read_b64 v[48:49], v73 offset:53824
	ds_read_b64 v[50:51], v73 offset:53856
	s_waitcnt lgkmcnt(10)
	v_mfma_f32_16x16x32_bf16 v[36:39], v[52:55], v[78:81], 0
	ds_read_b64 v[52:53], v73 offset:62272
	ds_read_b64 v[54:55], v73 offset:62304
	s_waitcnt lgkmcnt(10)
	v_mfma_f32_16x16x32_bf16 v[40:43], v[56:59], v[78:81], 0
	ds_read_b64 v[56:57], v73 offset:36992
	ds_read_b64 v[58:59], v73 offset:37024
	s_waitcnt lgkmcnt(10)
	v_mfma_f32_16x16x32_bf16 v[44:47], v[60:63], v[78:81], 0
	ds_read_b64 v[60:61], v73 offset:45440
	ds_read_b64 v[62:63], v73 offset:45472
	s_waitcnt lgkmcnt(10)
	v_mfma_f32_16x16x32_bf16 v[32:35], v[64:67], v[86:89], v[32:35]
	ds_read_b64 v[64:65], v73 offset:53888
	ds_read_b64 v[66:67], v73 offset:53920
	s_waitcnt lgkmcnt(10)
	v_mfma_f32_16x16x32_bf16 v[36:39], v[68:71], v[86:89], v[36:39]
	ds_read_b64 v[68:69], v73 offset:62336
	ds_read_b64 v[70:71], v73 offset:62368
	s_waitcnt lgkmcnt(10)
	v_mfma_f32_16x16x32_bf16 v[40:43], v[48:51], v[86:89], v[40:43]
	ds_read_b64 v[48:49], v73 offset:37056
	ds_read_b64 v[50:51], v73 offset:37088
	s_waitcnt lgkmcnt(10)
	v_mfma_f32_16x16x32_bf16 v[44:47], v[52:55], v[86:89], v[44:47]
	ds_read_b64 v[52:53], v73 offset:45504
	ds_read_b64 v[54:55], v73 offset:45536
	s_waitcnt lgkmcnt(10)
	v_mfma_f32_16x16x32_bf16 v[32:35], v[56:59], v[94:97], v[32:35]
	ds_read_b64 v[56:57], v73 offset:53952
	ds_read_b64 v[58:59], v73 offset:53984
	s_waitcnt lgkmcnt(10)
	v_mfma_f32_16x16x32_bf16 v[36:39], v[60:63], v[94:97], v[36:39]
	ds_read_b64 v[60:61], v73 offset:62400
	ds_read_b64 v[62:63], v73 offset:62432
	s_waitcnt lgkmcnt(10)
	v_mfma_f32_16x16x32_bf16 v[40:43], v[64:67], v[94:97], v[40:43]
	ds_read_b64 v[64:65], v73 offset:37120
	ds_read_b64 v[66:67], v73 offset:37152
	s_waitcnt lgkmcnt(10)
	v_mfma_f32_16x16x32_bf16 v[44:47], v[68:71], v[94:97], v[44:47]
	ds_read_b64 v[68:69], v73 offset:45568
	ds_read_b64 v[70:71], v73 offset:45600
	s_waitcnt lgkmcnt(10)
	v_mfma_f32_16x16x32_bf16 v[32:35], v[48:51], v[102:105], v[32:35]
	ds_read_b64 v[48:49], v73 offset:54016
	ds_read_b64 v[50:51], v73 offset:54048
	s_waitcnt lgkmcnt(10)
	v_mfma_f32_16x16x32_bf16 v[36:39], v[52:55], v[102:105], v[36:39]
	ds_read_b64 v[52:53], v73 offset:62464
	ds_read_b64 v[54:55], v73 offset:62496
	s_waitcnt lgkmcnt(10)
	v_mfma_f32_16x16x32_bf16 v[40:43], v[56:59], v[102:105], v[40:43]
	ds_read_b64 v[56:57], v73 offset:37184
	ds_read_b64 v[58:59], v73 offset:37216
	s_waitcnt lgkmcnt(10)
	v_mfma_f32_16x16x32_bf16 v[44:47], v[60:63], v[102:105], v[44:47]
	ds_read_b64 v[60:61], v73 offset:45632
	ds_read_b64 v[62:63], v73 offset:45664
	s_waitcnt lgkmcnt(10)
	v_mfma_f32_16x16x32_bf16 v[32:35], v[64:67], v[110:113], v[32:35]
	ds_read_b64 v[64:65], v73 offset:54080
	ds_read_b64 v[66:67], v73 offset:54112
	s_waitcnt lgkmcnt(10)
	v_mfma_f32_16x16x32_bf16 v[36:39], v[68:71], v[110:113], v[36:39]
	ds_read_b64 v[68:69], v73 offset:62528
	ds_read_b64 v[70:71], v73 offset:62560
	s_waitcnt lgkmcnt(10)
	v_mfma_f32_16x16x32_bf16 v[40:43], v[48:51], v[110:113], v[40:43]
	ds_read_b64 v[48:49], v73 offset:37248
	ds_read_b64 v[50:51], v73 offset:37280
	s_waitcnt lgkmcnt(10)
	v_mfma_f32_16x16x32_bf16 v[44:47], v[52:55], v[110:113], v[44:47]
	ds_read_b64 v[52:53], v73 offset:45696
	ds_read_b64 v[54:55], v73 offset:45728
	s_waitcnt lgkmcnt(10)
	v_mfma_f32_16x16x32_bf16 v[32:35], v[56:59], v[118:121], v[32:35]
	ds_read_b64 v[56:57], v73 offset:54144
	ds_read_b64 v[58:59], v73 offset:54176
	s_waitcnt lgkmcnt(10)
	v_mfma_f32_16x16x32_bf16 v[36:39], v[60:63], v[118:121], v[36:39]
	ds_read_b64 v[60:61], v73 offset:62592
	ds_read_b64 v[62:63], v73 offset:62624
	s_waitcnt lgkmcnt(10)
	v_mfma_f32_16x16x32_bf16 v[40:43], v[64:67], v[118:121], v[40:43]
	ds_read_b64 v[64:65], v73 offset:37312
	ds_read_b64 v[66:67], v73 offset:37344
	s_waitcnt lgkmcnt(10)
	v_mfma_f32_16x16x32_bf16 v[44:47], v[68:71], v[118:121], v[44:47]
	ds_read_b64 v[68:69], v73 offset:45760
	ds_read_b64 v[70:71], v73 offset:45792
	s_waitcnt lgkmcnt(10)
	v_mfma_f32_16x16x32_bf16 v[32:35], v[48:51], v[126:129], v[32:35]
	ds_read_b64 v[48:49], v73 offset:54208
	ds_read_b64 v[50:51], v73 offset:54240
	s_waitcnt lgkmcnt(10)
	v_mfma_f32_16x16x32_bf16 v[36:39], v[52:55], v[126:129], v[36:39]
	ds_read_b64 v[52:53], v73 offset:62656
	ds_read_b64 v[54:55], v73 offset:62688
	s_waitcnt lgkmcnt(10)
	v_mfma_f32_16x16x32_bf16 v[40:43], v[56:59], v[126:129], v[40:43]
	s_waitcnt lgkmcnt(8)
	v_mfma_f32_16x16x32_bf16 v[44:47], v[60:63], v[126:129], v[44:47]
	s_waitcnt lgkmcnt(6)
	v_mfma_f32_16x16x32_bf16 v[32:35], v[64:67], v[134:137], v[32:35]
	s_waitcnt lgkmcnt(4)
	v_mfma_f32_16x16x32_bf16 v[36:39], v[68:71], v[134:137], v[36:39]
	s_waitcnt lgkmcnt(2)
	v_mfma_f32_16x16x32_bf16 v[40:43], v[48:51], v[134:137], v[40:43]
	s_waitcnt lgkmcnt(0)
	v_mfma_f32_16x16x32_bf16 v[44:47], v[52:55], v[134:137], v[44:47]
	s_add_u32 s16, s12, 0x0
	s_addc_u32 s17, s13, 0
	s_nop 7
	v_pk_mul_f32 v[32:33], v[32:33], v[142:143]
	v_pk_mul_f32 v[34:35], v[34:35], v[142:143]
	v_pk_mul_f32 v[36:37], v[36:37], v[142:143]
	v_pk_mul_f32 v[38:39], v[38:39], v[142:143]
	v_pk_mul_f32 v[40:41], v[40:41], v[142:143]
	v_pk_mul_f32 v[42:43], v[42:43], v[142:143]
	v_pk_mul_f32 v[44:45], v[44:45], v[142:143]
	v_pk_mul_f32 v[46:47], v[46:47], v[142:143]
	v_cvt_pk_bf16_f32 v32, v32, v33
	v_cvt_pk_bf16_f32 v33, v34, v35
	v_cvt_pk_bf16_f32 v36, v36, v37
	v_cvt_pk_bf16_f32 v37, v38, v39
	v_cvt_pk_bf16_f32 v40, v40, v41
	v_cvt_pk_bf16_f32 v41, v42, v43
	v_cvt_pk_bf16_f32 v44, v44, v45
	v_cvt_pk_bf16_f32 v45, v46, v47
	global_store_dwordx2 v74, v[32:33], s[16:17] offset:0
	global_store_dwordx2 v74, v[36:37], s[16:17] offset:32
	global_store_dwordx2 v74, v[40:41], s[16:17] offset:64
	global_store_dwordx2 v74, v[44:45], s[16:17] offset:96
	ds_read_b128 v[48:51], v72 offset:0
	ds_read_b128 v[52:55], v72 offset:64
	ds_read_b128 v[56:59], v72 offset:2304
	ds_read_b128 v[60:63], v72 offset:2368
	ds_read_b128 v[64:67], v72 offset:4608
	ds_read_b128 v[68:71], v72 offset:4672
	s_waitcnt lgkmcnt(5)
	v_mfma_f32_16x16x32_bf16 v[78:81], v[48:51], v[8:11], 0
	ds_read_b128 v[48:51], v72 offset:6912
	s_waitcnt lgkmcnt(5)
	v_mfma_f32_16x16x32_bf16 v[78:81], v[52:55], v[12:15], v[78:81]
	ds_read_b128 v[52:55], v72 offset:6976
	s_waitcnt lgkmcnt(5)
	v_mfma_f32_16x16x32_bf16 v[82:85], v[56:59], v[8:11], 0
	ds_read_b128 v[56:59], v72 offset:9216
	s_waitcnt lgkmcnt(5)
	v_mfma_f32_16x16x32_bf16 v[82:85], v[60:63], v[12:15], v[82:85]
	ds_read_b128 v[60:63], v72 offset:9280
	s_waitcnt lgkmcnt(5)
	v_mfma_f32_16x16x32_bf16 v[86:89], v[64:67], v[8:11], 0
	ds_read_b128 v[64:67], v72 offset:11520
	s_waitcnt lgkmcnt(5)
	v_mfma_f32_16x16x32_bf16 v[86:89], v[68:71], v[12:15], v[86:89]
	ds_read_b128 v[68:71], v72 offset:11584
	s_waitcnt lgkmcnt(5)
	v_mfma_f32_16x16x32_bf16 v[90:93], v[48:51], v[8:11], 0
	ds_read_b128 v[48:51], v72 offset:13824
	s_waitcnt lgkmcnt(5)
	v_mfma_f32_16x16x32_bf16 v[90:93], v[52:55], v[12:15], v[90:93]
	ds_read_b128 v[52:55], v72 offset:13888
	s_waitcnt lgkmcnt(5)
	v_mfma_f32_16x16x32_bf16 v[94:97], v[56:59], v[8:11], 0
	ds_read_b128 v[56:59], v72 offset:16128
	s_waitcnt lgkmcnt(5)
	v_mfma_f32_16x16x32_bf16 v[94:97], v[60:63], v[12:15], v[94:97]
	ds_read_b128 v[60:63], v72 offset:16192
	s_waitcnt lgkmcnt(5)
	v_mfma_f32_16x16x32_bf16 v[98:101], v[64:67], v[8:11], 0
	ds_read_b128 v[64:67], v72 offset:18432
	s_waitcnt lgkmcnt(5)
	v_mfma_f32_16x16x32_bf16 v[98:101], v[68:71], v[12:15], v[98:101]
	ds_read_b128 v[68:71], v72 offset:18496
	s_waitcnt lgkmcnt(5)
	v_mfma_f32_16x16x32_bf16 v[102:105], v[48:51], v[8:11], 0
	ds_read_b128 v[48:51], v72 offset:20736
	s_waitcnt lgkmcnt(5)
	v_mfma_f32_16x16x32_bf16 v[102:105], v[52:55], v[12:15], v[102:105]
	ds_read_b128 v[52:55], v72 offset:20800
	s_waitcnt lgkmcnt(5)
	v_mfma_f32_16x16x32_bf16 v[106:109], v[56:59], v[8:11], 0
	ds_read_b128 v[56:59], v72 offset:23040
	s_waitcnt lgkmcnt(5)
	v_mfma_f32_16x16x32_bf16 v[106:109], v[60:63], v[12:15], v[106:109]
	ds_read_b128 v[60:63], v72 offset:23104
	s_waitcnt lgkmcnt(5)
	v_mfma_f32_16x16x32_bf16 v[110:113], v[64:67], v[8:11], 0
	ds_read_b128 v[64:67], v72 offset:25344
	s_waitcnt lgkmcnt(5)
	v_mfma_f32_16x16x32_bf16 v[110:113], v[68:71], v[12:15], v[110:113]
	ds_read_b128 v[68:71], v72 offset:25408
	s_waitcnt lgkmcnt(5)
	v_mfma_f32_16x16x32_bf16 v[114:117], v[48:51], v[8:11], 0
	ds_read_b128 v[48:51], v72 offset:27648
	s_waitcnt lgkmcnt(5)
	v_mfma_f32_16x16x32_bf16 v[114:117], v[52:55], v[12:15], v[114:117]
	ds_read_b128 v[52:55], v72 offset:27712
	s_waitcnt lgkmcnt(5)
	v_mfma_f32_16x16x32_bf16 v[118:121], v[56:59], v[8:11], 0
	ds_read_b128 v[56:59], v72 offset:29952
	s_waitcnt lgkmcnt(5)
	v_mfma_f32_16x16x32_bf16 v[118:121], v[60:63], v[12:15], v[118:121]
	ds_read_b128 v[60:63], v72 offset:30016
	s_waitcnt lgkmcnt(5)
	v_mfma_f32_16x16x32_bf16 v[122:125], v[64:67], v[8:11], 0
	ds_read_b128 v[64:67], v72 offset:32256
	s_waitcnt lgkmcnt(5)
	v_mfma_f32_16x16x32_bf16 v[122:125], v[68:71], v[12:15], v[122:125]
	ds_read_b128 v[68:71], v72 offset:32320
	s_waitcnt lgkmcnt(5)
	v_mfma_f32_16x16x32_bf16 v[126:129], v[48:51], v[8:11], 0
	ds_read_b128 v[48:51], v72 offset:34560
	s_waitcnt lgkmcnt(5)
	v_mfma_f32_16x16x32_bf16 v[126:129], v[52:55], v[12:15], v[126:129]
	ds_read_b128 v[52:55], v72 offset:34624
	s_waitcnt lgkmcnt(5)
	v_mfma_f32_16x16x32_bf16 v[130:133], v[56:59], v[8:11], 0
	s_waitcnt lgkmcnt(4)
	v_mfma_f32_16x16x32_bf16 v[130:133], v[60:63], v[12:15], v[130:133]
	s_waitcnt lgkmcnt(3)
	v_mfma_f32_16x16x32_bf16 v[134:137], v[64:67], v[8:11], 0
	s_waitcnt lgkmcnt(2)
	v_mfma_f32_16x16x32_bf16 v[134:137], v[68:71], v[12:15], v[134:137]
	s_waitcnt lgkmcnt(1)
	v_mfma_f32_16x16x32_bf16 v[138:141], v[48:51], v[8:11], 0
	s_waitcnt lgkmcnt(0)
	v_mfma_f32_16x16x32_bf16 v[138:141], v[52:55], v[12:15], v[138:141]
	v_max3_f32 v36, v78, v79, v80
	v_max3_f32 v36, v36, v81, v82
	v_max3_f32 v36, v36, v83, v84
	v_max3_f32 v36, v36, v85, v86
	v_max3_f32 v36, v36, v87, v88
	v_max3_f32 v36, v36, v89, v90
	v_max3_f32 v36, v36, v91, v92
	v_max3_f32 v36, v36, v93, v94
	v_max3_f32 v36, v36, v95, v96
	v_max3_f32 v36, v36, v97, v98
	v_max3_f32 v36, v36, v99, v100
	v_max3_f32 v36, v36, v101, v102
	v_max3_f32 v36, v36, v103, v104
	v_max3_f32 v36, v36, v105, v106
	v_max3_f32 v36, v36, v107, v108
	v_max3_f32 v36, v36, v109, v110
	v_max3_f32 v36, v36, v111, v112
	v_max3_f32 v36, v36, v113, v114
	v_max3_f32 v36, v36, v115, v116
	v_max3_f32 v36, v36, v117, v118
	v_max3_f32 v36, v36, v119, v120
	v_max3_f32 v36, v36, v121, v122
	v_max3_f32 v36, v36, v123, v124
	v_max3_f32 v36, v36, v125, v126
	v_max3_f32 v36, v36, v127, v128
	v_max3_f32 v36, v36, v129, v130
	v_max3_f32 v36, v36, v131, v132
	v_max3_f32 v36, v36, v133, v134
	v_max3_f32 v36, v36, v135, v136
	v_max3_f32 v36, v36, v137, v138
	v_max3_f32 v36, v36, v139, v140
	v_max_f32_e32 v36, v36, v141
	ds_bpermute_b32 v37, v75, v36
	s_waitcnt lgkmcnt(0)
	v_max_f32_e32 v36, v36, v37
	ds_bpermute_b32 v37, v77, v36
	s_waitcnt lgkmcnt(0)
	v_max_f32_e32 v36, v36, v37
	v_mul_f32_e64 v34, v36, -v144
	v_mov_b32_e32 v32, 0
	v_mov_b32_e32 v33, 0
	v_mov_b32_e32 v35, v34
	v_pk_fma_f32 v[78:79], v[78:79], v[144:145], v[34:35]
	v_pk_fma_f32 v[80:81], v[80:81], v[144:145], v[34:35]
	v_exp_f32_e32 v78, v78
	v_exp_f32_e32 v79, v79
	v_exp_f32_e32 v80, v80
	v_exp_f32_e32 v81, v81
	v_pk_fma_f32 v[82:83], v[82:83], v[144:145], v[34:35]
	v_pk_fma_f32 v[84:85], v[84:85], v[144:145], v[34:35]
	v_exp_f32_e32 v82, v82
	v_exp_f32_e32 v83, v83
	v_exp_f32_e32 v84, v84
	v_exp_f32_e32 v85, v85
	v_pk_add_f32 v[32:33], v[32:33], v[78:79]
	v_pk_add_f32 v[32:33], v[32:33], v[80:81]
	v_pk_fma_f32 v[86:87], v[86:87], v[144:145], v[34:35]
	v_pk_fma_f32 v[88:89], v[88:89], v[144:145], v[34:35]
	v_exp_f32_e32 v86, v86
	v_exp_f32_e32 v87, v87
	v_exp_f32_e32 v88, v88
	v_exp_f32_e32 v89, v89
	v_pk_add_f32 v[32:33], v[32:33], v[82:83]
	v_pk_add_f32 v[32:33], v[32:33], v[84:85]
	v_pk_fma_f32 v[90:91], v[90:91], v[144:145], v[34:35]
	v_pk_fma_f32 v[92:93], v[92:93], v[144:145], v[34:35]
	v_exp_f32_e32 v90, v90
	v_exp_f32_e32 v91, v91
	v_exp_f32_e32 v92, v92
	v_exp_f32_e32 v93, v93
	v_pk_add_f32 v[32:33], v[32:33], v[86:87]
	v_pk_add_f32 v[32:33], v[32:33], v[88:89]
	v_pk_fma_f32 v[94:95], v[94:95], v[144:145], v[34:35]
	v_pk_fma_f32 v[96:97], v[96:97], v[144:145], v[34:35]
	v_exp_f32_e32 v94, v94
	v_exp_f32_e32 v95, v95
	v_exp_f32_e32 v96, v96
	v_exp_f32_e32 v97, v97
	v_pk_add_f32 v[32:33], v[32:33], v[90:91]
	v_pk_add_f32 v[32:33], v[32:33], v[92:93]
	v_pk_fma_f32 v[98:99], v[98:99], v[144:145], v[34:35]
	v_pk_fma_f32 v[100:101], v[100:101], v[144:145], v[34:35]
	v_exp_f32_e32 v98, v98
	v_exp_f32_e32 v99, v99
	v_exp_f32_e32 v100, v100
	v_exp_f32_e32 v101, v101
	v_pk_add_f32 v[32:33], v[32:33], v[94:95]
	v_pk_add_f32 v[32:33], v[32:33], v[96:97]
	v_pk_fma_f32 v[102:103], v[102:103], v[144:145], v[34:35]
	v_pk_fma_f32 v[104:105], v[104:105], v[144:145], v[34:35]
	v_exp_f32_e32 v102, v102
	v_exp_f32_e32 v103, v103
	v_exp_f32_e32 v104, v104
	v_exp_f32_e32 v105, v105
	v_pk_add_f32 v[32:33], v[32:33], v[98:99]
	v_pk_add_f32 v[32:33], v[32:33], v[100:101]
	v_pk_fma_f32 v[106:107], v[106:107], v[144:145], v[34:35]
	v_pk_fma_f32 v[108:109], v[108:109], v[144:145], v[34:35]
	v_exp_f32_e32 v106, v106
	v_exp_f32_e32 v107, v107
	v_exp_f32_e32 v108, v108
	v_exp_f32_e32 v109, v109
	v_pk_add_f32 v[32:33], v[32:33], v[102:103]
	v_pk_add_f32 v[32:33], v[32:33], v[104:105]
	v_pk_fma_f32 v[110:111], v[110:111], v[144:145], v[34:35]
	v_pk_fma_f32 v[112:113], v[112:113], v[144:145], v[34:35]
	v_exp_f32_e32 v110, v110
	v_exp_f32_e32 v111, v111
	v_exp_f32_e32 v112, v112
	v_exp_f32_e32 v113, v113
	v_pk_add_f32 v[32:33], v[32:33], v[106:107]
	v_pk_add_f32 v[32:33], v[32:33], v[108:109]
	v_pk_fma_f32 v[114:115], v[114:115], v[144:145], v[34:35]
	v_pk_fma_f32 v[116:117], v[116:117], v[144:145], v[34:35]
	v_exp_f32_e32 v114, v114
	v_exp_f32_e32 v115, v115
	v_exp_f32_e32 v116, v116
	v_exp_f32_e32 v117, v117
	v_pk_add_f32 v[32:33], v[32:33], v[110:111]
	v_pk_add_f32 v[32:33], v[32:33], v[112:113]
	v_pk_fma_f32 v[118:119], v[118:119], v[144:145], v[34:35]
	v_pk_fma_f32 v[120:121], v[120:121], v[144:145], v[34:35]
	v_exp_f32_e32 v118, v118
	v_exp_f32_e32 v119, v119
	v_exp_f32_e32 v120, v120
	v_exp_f32_e32 v121, v121
	v_pk_add_f32 v[32:33], v[32:33], v[114:115]
	v_pk_add_f32 v[32:33], v[32:33], v[116:117]
	v_pk_fma_f32 v[122:123], v[122:123], v[144:145], v[34:35]
	v_pk_fma_f32 v[124:125], v[124:125], v[144:145], v[34:35]
	v_exp_f32_e32 v122, v122
	v_exp_f32_e32 v123, v123
	v_exp_f32_e32 v124, v124
	v_exp_f32_e32 v125, v125
	v_pk_add_f32 v[32:33], v[32:33], v[118:119]
	v_pk_add_f32 v[32:33], v[32:33], v[120:121]
	v_pk_fma_f32 v[126:127], v[126:127], v[144:145], v[34:35]
	v_pk_fma_f32 v[128:129], v[128:129], v[144:145], v[34:35]
	v_exp_f32_e32 v126, v126
	v_exp_f32_e32 v127, v127
	v_exp_f32_e32 v128, v128
	v_exp_f32_e32 v129, v129
	v_pk_add_f32 v[32:33], v[32:33], v[122:123]
	v_pk_add_f32 v[32:33], v[32:33], v[124:125]
	v_pk_fma_f32 v[130:131], v[130:131], v[144:145], v[34:35]
	v_pk_fma_f32 v[132:133], v[132:133], v[144:145], v[34:35]
	v_exp_f32_e32 v130, v130
	v_exp_f32_e32 v131, v131
	v_exp_f32_e32 v132, v132
	v_exp_f32_e32 v133, v133
	v_pk_add_f32 v[32:33], v[32:33], v[126:127]
	v_pk_add_f32 v[32:33], v[32:33], v[128:129]
	v_pk_fma_f32 v[134:135], v[134:135], v[144:145], v[34:35]
	v_pk_fma_f32 v[136:137], v[136:137], v[144:145], v[34:35]
	v_exp_f32_e32 v134, v134
	v_exp_f32_e32 v135, v135
	v_exp_f32_e32 v136, v136
	v_exp_f32_e32 v137, v137
	v_pk_add_f32 v[32:33], v[32:33], v[130:131]
	v_pk_add_f32 v[32:33], v[32:33], v[132:133]
	v_pk_fma_f32 v[138:139], v[138:139], v[144:145], v[34:35]
	v_pk_fma_f32 v[140:141], v[140:141], v[144:145], v[34:35]
	v_exp_f32_e32 v138, v138
	v_exp_f32_e32 v139, v139
	v_exp_f32_e32 v140, v140
	v_exp_f32_e32 v141, v141
	v_pk_add_f32 v[32:33], v[32:33], v[134:135]
	v_pk_add_f32 v[32:33], v[32:33], v[136:137]
	s_nop 0
	v_pk_add_f32 v[32:33], v[32:33], v[138:139]
	v_pk_add_f32 v[32:33], v[32:33], v[140:141]
	v_add_f32_e32 v36, v32, v33
	ds_bpermute_b32 v37, v75, v36
	v_cvt_pk_bf16_f32 v78, v78, v79
	v_cvt_pk_bf16_f32 v79, v80, v81
	v_cvt_pk_bf16_f32 v80, v82, v83
	v_cvt_pk_bf16_f32 v81, v84, v85
	v_cvt_pk_bf16_f32 v86, v86, v87
	v_cvt_pk_bf16_f32 v87, v88, v89
	v_cvt_pk_bf16_f32 v88, v90, v91
	v_cvt_pk_bf16_f32 v89, v92, v93
	v_cvt_pk_bf16_f32 v94, v94, v95
	v_cvt_pk_bf16_f32 v95, v96, v97
	v_cvt_pk_bf16_f32 v96, v98, v99
	v_cvt_pk_bf16_f32 v97, v100, v101
	v_cvt_pk_bf16_f32 v102, v102, v103
	v_cvt_pk_bf16_f32 v103, v104, v105
	v_cvt_pk_bf16_f32 v104, v106, v107
	v_cvt_pk_bf16_f32 v105, v108, v109
	v_cvt_pk_bf16_f32 v110, v110, v111
	v_cvt_pk_bf16_f32 v111, v112, v113
	v_cvt_pk_bf16_f32 v112, v114, v115
	v_cvt_pk_bf16_f32 v113, v116, v117
	v_cvt_pk_bf16_f32 v118, v118, v119
	v_cvt_pk_bf16_f32 v119, v120, v121
	v_cvt_pk_bf16_f32 v120, v122, v123
	v_cvt_pk_bf16_f32 v121, v124, v125
	v_cvt_pk_bf16_f32 v126, v126, v127
	v_cvt_pk_bf16_f32 v127, v128, v129
	v_cvt_pk_bf16_f32 v128, v130, v131
	v_cvt_pk_bf16_f32 v129, v132, v133
	v_cvt_pk_bf16_f32 v134, v134, v135
	v_cvt_pk_bf16_f32 v135, v136, v137
	v_cvt_pk_bf16_f32 v136, v138, v139
	v_cvt_pk_bf16_f32 v137, v140, v141
	s_waitcnt lgkmcnt(0)
	v_add_f32_e32 v36, v36, v37
	ds_bpermute_b32 v37, v77, v36
	ds_read_b64 v[48:49], v73 offset:36864
	ds_read_b64 v[50:51], v73 offset:36896
	ds_read_b64 v[52:53], v73 offset:45312
	ds_read_b64 v[54:55], v73 offset:45344
	ds_read_b64 v[56:57], v73 offset:53760
	ds_read_b64 v[58:59], v73 offset:53792
	ds_read_b64 v[60:61], v73 offset:62208
	ds_read_b64 v[62:63], v73 offset:62240
	ds_read_b64 v[64:65], v73 offset:36928
	ds_read_b64 v[66:67], v73 offset:36960
	s_waitcnt lgkmcnt(10)
	v_add_f32_e32 v36, v36, v37
	v_rcp_f32_e32 v142, v36
	s_nop 0
	v_fma_f32 v143, -v36, v142, 1.0
	v_fma_f32 v142, v143, v142, v142
	v_mov_b32_e32 v143, v142
	ds_read_b64 v[68:69], v73 offset:45376
	ds_read_b64 v[70:71], v73 offset:45408
	s_waitcnt lgkmcnt(10)
	v_mfma_f32_16x16x32_bf16 v[32:35], v[48:51], v[78:81], 0
	ds_read_b64 v[48:49], v73 offset:53824
	ds_read_b64 v[50:51], v73 offset:53856
	s_waitcnt lgkmcnt(10)
	v_mfma_f32_16x16x32_bf16 v[36:39], v[52:55], v[78:81], 0
	ds_read_b64 v[52:53], v73 offset:62272
	ds_read_b64 v[54:55], v73 offset:62304
	s_waitcnt lgkmcnt(10)
	v_mfma_f32_16x16x32_bf16 v[40:43], v[56:59], v[78:81], 0
	ds_read_b64 v[56:57], v73 offset:36992
	ds_read_b64 v[58:59], v73 offset:37024
	s_waitcnt lgkmcnt(10)
	v_mfma_f32_16x16x32_bf16 v[44:47], v[60:63], v[78:81], 0
	ds_read_b64 v[60:61], v73 offset:45440
	ds_read_b64 v[62:63], v73 offset:45472
	s_waitcnt lgkmcnt(10)
	v_mfma_f32_16x16x32_bf16 v[32:35], v[64:67], v[86:89], v[32:35]
	ds_read_b64 v[64:65], v73 offset:53888
	ds_read_b64 v[66:67], v73 offset:53920
	s_waitcnt lgkmcnt(10)
	v_mfma_f32_16x16x32_bf16 v[36:39], v[68:71], v[86:89], v[36:39]
	ds_read_b64 v[68:69], v73 offset:62336
	ds_read_b64 v[70:71], v73 offset:62368
	s_waitcnt lgkmcnt(10)
	v_mfma_f32_16x16x32_bf16 v[40:43], v[48:51], v[86:89], v[40:43]
	ds_read_b64 v[48:49], v73 offset:37056
	ds_read_b64 v[50:51], v73 offset:37088
	s_waitcnt lgkmcnt(10)
	v_mfma_f32_16x16x32_bf16 v[44:47], v[52:55], v[86:89], v[44:47]
	ds_read_b64 v[52:53], v73 offset:45504
	ds_read_b64 v[54:55], v73 offset:45536
	s_waitcnt lgkmcnt(10)
	v_mfma_f32_16x16x32_bf16 v[32:35], v[56:59], v[94:97], v[32:35]
	ds_read_b64 v[56:57], v73 offset:53952
	ds_read_b64 v[58:59], v73 offset:53984
	s_waitcnt lgkmcnt(10)
	v_mfma_f32_16x16x32_bf16 v[36:39], v[60:63], v[94:97], v[36:39]
	ds_read_b64 v[60:61], v73 offset:62400
	ds_read_b64 v[62:63], v73 offset:62432
	s_waitcnt lgkmcnt(10)
	v_mfma_f32_16x16x32_bf16 v[40:43], v[64:67], v[94:97], v[40:43]
	ds_read_b64 v[64:65], v73 offset:37120
	ds_read_b64 v[66:67], v73 offset:37152
	s_waitcnt lgkmcnt(10)
	v_mfma_f32_16x16x32_bf16 v[44:47], v[68:71], v[94:97], v[44:47]
	ds_read_b64 v[68:69], v73 offset:45568
	ds_read_b64 v[70:71], v73 offset:45600
	s_waitcnt lgkmcnt(10)
	v_mfma_f32_16x16x32_bf16 v[32:35], v[48:51], v[102:105], v[32:35]
	ds_read_b64 v[48:49], v73 offset:54016
	ds_read_b64 v[50:51], v73 offset:54048
	s_waitcnt lgkmcnt(10)
	v_mfma_f32_16x16x32_bf16 v[36:39], v[52:55], v[102:105], v[36:39]
	ds_read_b64 v[52:53], v73 offset:62464
	ds_read_b64 v[54:55], v73 offset:62496
	s_waitcnt lgkmcnt(10)
	v_mfma_f32_16x16x32_bf16 v[40:43], v[56:59], v[102:105], v[40:43]
	ds_read_b64 v[56:57], v73 offset:37184
	ds_read_b64 v[58:59], v73 offset:37216
	s_waitcnt lgkmcnt(10)
	v_mfma_f32_16x16x32_bf16 v[44:47], v[60:63], v[102:105], v[44:47]
	ds_read_b64 v[60:61], v73 offset:45632
	ds_read_b64 v[62:63], v73 offset:45664
	s_waitcnt lgkmcnt(10)
	v_mfma_f32_16x16x32_bf16 v[32:35], v[64:67], v[110:113], v[32:35]
	ds_read_b64 v[64:65], v73 offset:54080
	ds_read_b64 v[66:67], v73 offset:54112
	s_waitcnt lgkmcnt(10)
	v_mfma_f32_16x16x32_bf16 v[36:39], v[68:71], v[110:113], v[36:39]
	ds_read_b64 v[68:69], v73 offset:62528
	ds_read_b64 v[70:71], v73 offset:62560
	s_waitcnt lgkmcnt(10)
	v_mfma_f32_16x16x32_bf16 v[40:43], v[48:51], v[110:113], v[40:43]
	ds_read_b64 v[48:49], v73 offset:37248
	ds_read_b64 v[50:51], v73 offset:37280
	s_waitcnt lgkmcnt(10)
	v_mfma_f32_16x16x32_bf16 v[44:47], v[52:55], v[110:113], v[44:47]
	ds_read_b64 v[52:53], v73 offset:45696
	ds_read_b64 v[54:55], v73 offset:45728
	s_waitcnt lgkmcnt(10)
	v_mfma_f32_16x16x32_bf16 v[32:35], v[56:59], v[118:121], v[32:35]
	ds_read_b64 v[56:57], v73 offset:54144
	ds_read_b64 v[58:59], v73 offset:54176
	s_waitcnt lgkmcnt(10)
	v_mfma_f32_16x16x32_bf16 v[36:39], v[60:63], v[118:121], v[36:39]
	ds_read_b64 v[60:61], v73 offset:62592
	ds_read_b64 v[62:63], v73 offset:62624
	s_waitcnt lgkmcnt(10)
	v_mfma_f32_16x16x32_bf16 v[40:43], v[64:67], v[118:121], v[40:43]
	ds_read_b64 v[64:65], v73 offset:37312
	ds_read_b64 v[66:67], v73 offset:37344
	s_waitcnt lgkmcnt(10)
	v_mfma_f32_16x16x32_bf16 v[44:47], v[68:71], v[118:121], v[44:47]
	ds_read_b64 v[68:69], v73 offset:45760
	ds_read_b64 v[70:71], v73 offset:45792
	s_waitcnt lgkmcnt(10)
	v_mfma_f32_16x16x32_bf16 v[32:35], v[48:51], v[126:129], v[32:35]
	ds_read_b64 v[48:49], v73 offset:54208
	ds_read_b64 v[50:51], v73 offset:54240
	s_waitcnt lgkmcnt(10)
	v_mfma_f32_16x16x32_bf16 v[36:39], v[52:55], v[126:129], v[36:39]
	ds_read_b64 v[52:53], v73 offset:62656
	ds_read_b64 v[54:55], v73 offset:62688
	s_waitcnt lgkmcnt(10)
	v_mfma_f32_16x16x32_bf16 v[40:43], v[56:59], v[126:129], v[40:43]
	s_waitcnt lgkmcnt(8)
	v_mfma_f32_16x16x32_bf16 v[44:47], v[60:63], v[126:129], v[44:47]
	s_waitcnt lgkmcnt(6)
	v_mfma_f32_16x16x32_bf16 v[32:35], v[64:67], v[134:137], v[32:35]
	s_waitcnt lgkmcnt(4)
	v_mfma_f32_16x16x32_bf16 v[36:39], v[68:71], v[134:137], v[36:39]
	s_waitcnt lgkmcnt(2)
	v_mfma_f32_16x16x32_bf16 v[40:43], v[48:51], v[134:137], v[40:43]
	s_waitcnt lgkmcnt(0)
	v_mfma_f32_16x16x32_bf16 v[44:47], v[52:55], v[134:137], v[44:47]
	s_add_u32 s16, s12, 0x8000
	s_addc_u32 s17, s13, 0
	s_nop 7
	v_pk_mul_f32 v[32:33], v[32:33], v[142:143]
	v_pk_mul_f32 v[34:35], v[34:35], v[142:143]
	v_pk_mul_f32 v[36:37], v[36:37], v[142:143]
	v_pk_mul_f32 v[38:39], v[38:39], v[142:143]
	v_pk_mul_f32 v[40:41], v[40:41], v[142:143]
	v_pk_mul_f32 v[42:43], v[42:43], v[142:143]
	v_pk_mul_f32 v[44:45], v[44:45], v[142:143]
	v_pk_mul_f32 v[46:47], v[46:47], v[142:143]
	v_cvt_pk_bf16_f32 v32, v32, v33
	v_cvt_pk_bf16_f32 v33, v34, v35
	v_cvt_pk_bf16_f32 v36, v36, v37
	v_cvt_pk_bf16_f32 v37, v38, v39
	v_cvt_pk_bf16_f32 v40, v40, v41
	v_cvt_pk_bf16_f32 v41, v42, v43
	v_cvt_pk_bf16_f32 v44, v44, v45
	v_cvt_pk_bf16_f32 v45, v46, v47
	global_store_dwordx2 v74, v[32:33], s[16:17] offset:0
	global_store_dwordx2 v74, v[36:37], s[16:17] offset:32
	global_store_dwordx2 v74, v[40:41], s[16:17] offset:64
	global_store_dwordx2 v74, v[44:45], s[16:17] offset:96
	ds_read_b128 v[48:51], v72 offset:0
	ds_read_b128 v[52:55], v72 offset:64
	ds_read_b128 v[56:59], v72 offset:2304
	ds_read_b128 v[60:63], v72 offset:2368
	ds_read_b128 v[64:67], v72 offset:4608
	ds_read_b128 v[68:71], v72 offset:4672
	s_waitcnt lgkmcnt(5)
	v_mfma_f32_16x16x32_bf16 v[78:81], v[48:51], v[16:19], 0
	ds_read_b128 v[48:51], v72 offset:6912
	s_waitcnt lgkmcnt(5)
	v_mfma_f32_16x16x32_bf16 v[78:81], v[52:55], v[20:23], v[78:81]
	ds_read_b128 v[52:55], v72 offset:6976
	s_waitcnt lgkmcnt(5)
	v_mfma_f32_16x16x32_bf16 v[82:85], v[56:59], v[16:19], 0
	ds_read_b128 v[56:59], v72 offset:9216
	s_waitcnt lgkmcnt(5)
	v_mfma_f32_16x16x32_bf16 v[82:85], v[60:63], v[20:23], v[82:85]
	ds_read_b128 v[60:63], v72 offset:9280
	s_waitcnt lgkmcnt(5)
	v_mfma_f32_16x16x32_bf16 v[86:89], v[64:67], v[16:19], 0
	ds_read_b128 v[64:67], v72 offset:11520
	s_waitcnt lgkmcnt(5)
	v_mfma_f32_16x16x32_bf16 v[86:89], v[68:71], v[20:23], v[86:89]
	ds_read_b128 v[68:71], v72 offset:11584
	s_waitcnt lgkmcnt(5)
	v_mfma_f32_16x16x32_bf16 v[90:93], v[48:51], v[16:19], 0
	ds_read_b128 v[48:51], v72 offset:13824
	s_waitcnt lgkmcnt(5)
	v_mfma_f32_16x16x32_bf16 v[90:93], v[52:55], v[20:23], v[90:93]
	ds_read_b128 v[52:55], v72 offset:13888
	s_waitcnt lgkmcnt(5)
	v_mfma_f32_16x16x32_bf16 v[94:97], v[56:59], v[16:19], 0
	ds_read_b128 v[56:59], v72 offset:16128
	s_waitcnt lgkmcnt(5)
	v_mfma_f32_16x16x32_bf16 v[94:97], v[60:63], v[20:23], v[94:97]
	ds_read_b128 v[60:63], v72 offset:16192
	s_waitcnt lgkmcnt(5)
	v_mfma_f32_16x16x32_bf16 v[98:101], v[64:67], v[16:19], 0
	ds_read_b128 v[64:67], v72 offset:18432
	s_waitcnt lgkmcnt(5)
	v_mfma_f32_16x16x32_bf16 v[98:101], v[68:71], v[20:23], v[98:101]
	ds_read_b128 v[68:71], v72 offset:18496
	s_waitcnt lgkmcnt(5)
	v_mfma_f32_16x16x32_bf16 v[102:105], v[48:51], v[16:19], 0
	ds_read_b128 v[48:51], v72 offset:20736
	s_waitcnt lgkmcnt(5)
	v_mfma_f32_16x16x32_bf16 v[102:105], v[52:55], v[20:23], v[102:105]
	ds_read_b128 v[52:55], v72 offset:20800
	s_waitcnt lgkmcnt(5)
	v_mfma_f32_16x16x32_bf16 v[106:109], v[56:59], v[16:19], 0
	ds_read_b128 v[56:59], v72 offset:23040
	s_waitcnt lgkmcnt(5)
	v_mfma_f32_16x16x32_bf16 v[106:109], v[60:63], v[20:23], v[106:109]
	ds_read_b128 v[60:63], v72 offset:23104
	s_waitcnt lgkmcnt(5)
	v_mfma_f32_16x16x32_bf16 v[110:113], v[64:67], v[16:19], 0
	ds_read_b128 v[64:67], v72 offset:25344
	s_waitcnt lgkmcnt(5)
	v_mfma_f32_16x16x32_bf16 v[110:113], v[68:71], v[20:23], v[110:113]
	ds_read_b128 v[68:71], v72 offset:25408
	s_waitcnt lgkmcnt(5)
	v_mfma_f32_16x16x32_bf16 v[114:117], v[48:51], v[16:19], 0
	ds_read_b128 v[48:51], v72 offset:27648
	s_waitcnt lgkmcnt(5)
	v_mfma_f32_16x16x32_bf16 v[114:117], v[52:55], v[20:23], v[114:117]
	ds_read_b128 v[52:55], v72 offset:27712
	s_waitcnt lgkmcnt(5)
	v_mfma_f32_16x16x32_bf16 v[118:121], v[56:59], v[16:19], 0
	ds_read_b128 v[56:59], v72 offset:29952
	s_waitcnt lgkmcnt(5)
	v_mfma_f32_16x16x32_bf16 v[118:121], v[60:63], v[20:23], v[118:121]
	ds_read_b128 v[60:63], v72 offset:30016
	s_waitcnt lgkmcnt(5)
	v_mfma_f32_16x16x32_bf16 v[122:125], v[64:67], v[16:19], 0
	ds_read_b128 v[64:67], v72 offset:32256
	s_waitcnt lgkmcnt(5)
	v_mfma_f32_16x16x32_bf16 v[122:125], v[68:71], v[20:23], v[122:125]
	ds_read_b128 v[68:71], v72 offset:32320
	s_waitcnt lgkmcnt(5)
	v_mfma_f32_16x16x32_bf16 v[126:129], v[48:51], v[16:19], 0
	ds_read_b128 v[48:51], v72 offset:34560
	s_waitcnt lgkmcnt(5)
	v_mfma_f32_16x16x32_bf16 v[126:129], v[52:55], v[20:23], v[126:129]
	ds_read_b128 v[52:55], v72 offset:34624
	s_waitcnt lgkmcnt(5)
	v_mfma_f32_16x16x32_bf16 v[130:133], v[56:59], v[16:19], 0
	s_waitcnt lgkmcnt(4)
	v_mfma_f32_16x16x32_bf16 v[130:133], v[60:63], v[20:23], v[130:133]
	s_waitcnt lgkmcnt(3)
	v_mfma_f32_16x16x32_bf16 v[134:137], v[64:67], v[16:19], 0
	s_waitcnt lgkmcnt(2)
	v_mfma_f32_16x16x32_bf16 v[134:137], v[68:71], v[20:23], v[134:137]
	s_waitcnt lgkmcnt(1)
	v_mfma_f32_16x16x32_bf16 v[138:141], v[48:51], v[16:19], 0
	s_waitcnt lgkmcnt(0)
	v_mfma_f32_16x16x32_bf16 v[138:141], v[52:55], v[20:23], v[138:141]
	v_max3_f32 v36, v78, v79, v80
	v_max3_f32 v36, v36, v81, v82
	v_max3_f32 v36, v36, v83, v84
	v_max3_f32 v36, v36, v85, v86
	v_max3_f32 v36, v36, v87, v88
	v_max3_f32 v36, v36, v89, v90
	v_max3_f32 v36, v36, v91, v92
	v_max3_f32 v36, v36, v93, v94
	v_max3_f32 v36, v36, v95, v96
	v_max3_f32 v36, v36, v97, v98
	v_max3_f32 v36, v36, v99, v100
	v_max3_f32 v36, v36, v101, v102
	v_max3_f32 v36, v36, v103, v104
	v_max3_f32 v36, v36, v105, v106
	v_max3_f32 v36, v36, v107, v108
	v_max3_f32 v36, v36, v109, v110
	v_max3_f32 v36, v36, v111, v112
	v_max3_f32 v36, v36, v113, v114
	v_max3_f32 v36, v36, v115, v116
	v_max3_f32 v36, v36, v117, v118
	v_max3_f32 v36, v36, v119, v120
	v_max3_f32 v36, v36, v121, v122
	v_max3_f32 v36, v36, v123, v124
	v_max3_f32 v36, v36, v125, v126
	v_max3_f32 v36, v36, v127, v128
	v_max3_f32 v36, v36, v129, v130
	v_max3_f32 v36, v36, v131, v132
	v_max3_f32 v36, v36, v133, v134
	v_max3_f32 v36, v36, v135, v136
	v_max3_f32 v36, v36, v137, v138
	v_max3_f32 v36, v36, v139, v140
	v_max_f32_e32 v36, v36, v141
	ds_bpermute_b32 v37, v75, v36
	s_waitcnt lgkmcnt(0)
	v_max_f32_e32 v36, v36, v37
	ds_bpermute_b32 v37, v77, v36
	s_waitcnt lgkmcnt(0)
	v_max_f32_e32 v36, v36, v37
	v_mul_f32_e64 v34, v36, -v144
	v_mov_b32_e32 v32, 0
	v_mov_b32_e32 v33, 0
	v_mov_b32_e32 v35, v34
	v_pk_fma_f32 v[78:79], v[78:79], v[144:145], v[34:35]
	v_pk_fma_f32 v[80:81], v[80:81], v[144:145], v[34:35]
	v_exp_f32_e32 v78, v78
	v_exp_f32_e32 v79, v79
	v_exp_f32_e32 v80, v80
	v_exp_f32_e32 v81, v81
	v_pk_fma_f32 v[82:83], v[82:83], v[144:145], v[34:35]
	v_pk_fma_f32 v[84:85], v[84:85], v[144:145], v[34:35]
	v_exp_f32_e32 v82, v82
	v_exp_f32_e32 v83, v83
	v_exp_f32_e32 v84, v84
	v_exp_f32_e32 v85, v85
	v_pk_add_f32 v[32:33], v[32:33], v[78:79]
	v_pk_add_f32 v[32:33], v[32:33], v[80:81]
	v_pk_fma_f32 v[86:87], v[86:87], v[144:145], v[34:35]
	v_pk_fma_f32 v[88:89], v[88:89], v[144:145], v[34:35]
	v_exp_f32_e32 v86, v86
	v_exp_f32_e32 v87, v87
	v_exp_f32_e32 v88, v88
	v_exp_f32_e32 v89, v89
	v_pk_add_f32 v[32:33], v[32:33], v[82:83]
	v_pk_add_f32 v[32:33], v[32:33], v[84:85]
	v_pk_fma_f32 v[90:91], v[90:91], v[144:145], v[34:35]
	v_pk_fma_f32 v[92:93], v[92:93], v[144:145], v[34:35]
	v_exp_f32_e32 v90, v90
	v_exp_f32_e32 v91, v91
	v_exp_f32_e32 v92, v92
	v_exp_f32_e32 v93, v93
	v_pk_add_f32 v[32:33], v[32:33], v[86:87]
	v_pk_add_f32 v[32:33], v[32:33], v[88:89]
	v_pk_fma_f32 v[94:95], v[94:95], v[144:145], v[34:35]
	v_pk_fma_f32 v[96:97], v[96:97], v[144:145], v[34:35]
	v_exp_f32_e32 v94, v94
	v_exp_f32_e32 v95, v95
	v_exp_f32_e32 v96, v96
	v_exp_f32_e32 v97, v97
	v_pk_add_f32 v[32:33], v[32:33], v[90:91]
	v_pk_add_f32 v[32:33], v[32:33], v[92:93]
	v_pk_fma_f32 v[98:99], v[98:99], v[144:145], v[34:35]
	v_pk_fma_f32 v[100:101], v[100:101], v[144:145], v[34:35]
	v_exp_f32_e32 v98, v98
	v_exp_f32_e32 v99, v99
	v_exp_f32_e32 v100, v100
	v_exp_f32_e32 v101, v101
	v_pk_add_f32 v[32:33], v[32:33], v[94:95]
	v_pk_add_f32 v[32:33], v[32:33], v[96:97]
	v_pk_fma_f32 v[102:103], v[102:103], v[144:145], v[34:35]
	v_pk_fma_f32 v[104:105], v[104:105], v[144:145], v[34:35]
	v_exp_f32_e32 v102, v102
	v_exp_f32_e32 v103, v103
	v_exp_f32_e32 v104, v104
	v_exp_f32_e32 v105, v105
	v_pk_add_f32 v[32:33], v[32:33], v[98:99]
	v_pk_add_f32 v[32:33], v[32:33], v[100:101]
	v_pk_fma_f32 v[106:107], v[106:107], v[144:145], v[34:35]
	v_pk_fma_f32 v[108:109], v[108:109], v[144:145], v[34:35]
	v_exp_f32_e32 v106, v106
	v_exp_f32_e32 v107, v107
	v_exp_f32_e32 v108, v108
	v_exp_f32_e32 v109, v109
	v_pk_add_f32 v[32:33], v[32:33], v[102:103]
	v_pk_add_f32 v[32:33], v[32:33], v[104:105]
	v_pk_fma_f32 v[110:111], v[110:111], v[144:145], v[34:35]
	v_pk_fma_f32 v[112:113], v[112:113], v[144:145], v[34:35]
	v_exp_f32_e32 v110, v110
	v_exp_f32_e32 v111, v111
	v_exp_f32_e32 v112, v112
	v_exp_f32_e32 v113, v113
	v_pk_add_f32 v[32:33], v[32:33], v[106:107]
	v_pk_add_f32 v[32:33], v[32:33], v[108:109]
	v_pk_fma_f32 v[114:115], v[114:115], v[144:145], v[34:35]
	v_pk_fma_f32 v[116:117], v[116:117], v[144:145], v[34:35]
	v_exp_f32_e32 v114, v114
	v_exp_f32_e32 v115, v115
	v_exp_f32_e32 v116, v116
	v_exp_f32_e32 v117, v117
	v_pk_add_f32 v[32:33], v[32:33], v[110:111]
	v_pk_add_f32 v[32:33], v[32:33], v[112:113]
	v_pk_fma_f32 v[118:119], v[118:119], v[144:145], v[34:35]
	v_pk_fma_f32 v[120:121], v[120:121], v[144:145], v[34:35]
	v_exp_f32_e32 v118, v118
	v_exp_f32_e32 v119, v119
	v_exp_f32_e32 v120, v120
	v_exp_f32_e32 v121, v121
	v_pk_add_f32 v[32:33], v[32:33], v[114:115]
	v_pk_add_f32 v[32:33], v[32:33], v[116:117]
	v_pk_fma_f32 v[122:123], v[122:123], v[144:145], v[34:35]
	v_pk_fma_f32 v[124:125], v[124:125], v[144:145], v[34:35]
	v_exp_f32_e32 v122, v122
	v_exp_f32_e32 v123, v123
	v_exp_f32_e32 v124, v124
	v_exp_f32_e32 v125, v125
	v_pk_add_f32 v[32:33], v[32:33], v[118:119]
	v_pk_add_f32 v[32:33], v[32:33], v[120:121]
	v_pk_fma_f32 v[126:127], v[126:127], v[144:145], v[34:35]
	v_pk_fma_f32 v[128:129], v[128:129], v[144:145], v[34:35]
	v_exp_f32_e32 v126, v126
	v_exp_f32_e32 v127, v127
	v_exp_f32_e32 v128, v128
	v_exp_f32_e32 v129, v129
	v_pk_add_f32 v[32:33], v[32:33], v[122:123]
	v_pk_add_f32 v[32:33], v[32:33], v[124:125]
	v_pk_fma_f32 v[130:131], v[130:131], v[144:145], v[34:35]
	v_pk_fma_f32 v[132:133], v[132:133], v[144:145], v[34:35]
	v_exp_f32_e32 v130, v130
	v_exp_f32_e32 v131, v131
	v_exp_f32_e32 v132, v132
	v_exp_f32_e32 v133, v133
	v_pk_add_f32 v[32:33], v[32:33], v[126:127]
	v_pk_add_f32 v[32:33], v[32:33], v[128:129]
	v_pk_fma_f32 v[134:135], v[134:135], v[144:145], v[34:35]
	v_pk_fma_f32 v[136:137], v[136:137], v[144:145], v[34:35]
	v_exp_f32_e32 v134, v134
	v_exp_f32_e32 v135, v135
	v_exp_f32_e32 v136, v136
	v_exp_f32_e32 v137, v137
	v_pk_add_f32 v[32:33], v[32:33], v[130:131]
	v_pk_add_f32 v[32:33], v[32:33], v[132:133]
	v_pk_fma_f32 v[138:139], v[138:139], v[144:145], v[34:35]
	v_pk_fma_f32 v[140:141], v[140:141], v[144:145], v[34:35]
	v_exp_f32_e32 v138, v138
	v_exp_f32_e32 v139, v139
	v_exp_f32_e32 v140, v140
	v_exp_f32_e32 v141, v141
	v_pk_add_f32 v[32:33], v[32:33], v[134:135]
	v_pk_add_f32 v[32:33], v[32:33], v[136:137]
	s_nop 0
	v_pk_add_f32 v[32:33], v[32:33], v[138:139]
	v_pk_add_f32 v[32:33], v[32:33], v[140:141]
	v_add_f32_e32 v36, v32, v33
	ds_bpermute_b32 v37, v75, v36
	v_cvt_pk_bf16_f32 v78, v78, v79
	v_cvt_pk_bf16_f32 v79, v80, v81
	v_cvt_pk_bf16_f32 v80, v82, v83
	v_cvt_pk_bf16_f32 v81, v84, v85
	v_cvt_pk_bf16_f32 v86, v86, v87
	v_cvt_pk_bf16_f32 v87, v88, v89
	v_cvt_pk_bf16_f32 v88, v90, v91
	v_cvt_pk_bf16_f32 v89, v92, v93
	v_cvt_pk_bf16_f32 v94, v94, v95
	v_cvt_pk_bf16_f32 v95, v96, v97
	v_cvt_pk_bf16_f32 v96, v98, v99
	v_cvt_pk_bf16_f32 v97, v100, v101
	v_cvt_pk_bf16_f32 v102, v102, v103
	v_cvt_pk_bf16_f32 v103, v104, v105
	v_cvt_pk_bf16_f32 v104, v106, v107
	v_cvt_pk_bf16_f32 v105, v108, v109
	v_cvt_pk_bf16_f32 v110, v110, v111
	v_cvt_pk_bf16_f32 v111, v112, v113
	v_cvt_pk_bf16_f32 v112, v114, v115
	v_cvt_pk_bf16_f32 v113, v116, v117
	v_cvt_pk_bf16_f32 v118, v118, v119
	v_cvt_pk_bf16_f32 v119, v120, v121
	v_cvt_pk_bf16_f32 v120, v122, v123
	v_cvt_pk_bf16_f32 v121, v124, v125
	v_cvt_pk_bf16_f32 v126, v126, v127
	v_cvt_pk_bf16_f32 v127, v128, v129
	v_cvt_pk_bf16_f32 v128, v130, v131
	v_cvt_pk_bf16_f32 v129, v132, v133
	v_cvt_pk_bf16_f32 v134, v134, v135
	v_cvt_pk_bf16_f32 v135, v136, v137
	v_cvt_pk_bf16_f32 v136, v138, v139
	v_cvt_pk_bf16_f32 v137, v140, v141
	s_waitcnt lgkmcnt(0)
	v_add_f32_e32 v36, v36, v37
	ds_bpermute_b32 v37, v77, v36
	ds_read_b64 v[48:49], v73 offset:36864
	ds_read_b64 v[50:51], v73 offset:36896
	ds_read_b64 v[52:53], v73 offset:45312
	ds_read_b64 v[54:55], v73 offset:45344
	ds_read_b64 v[56:57], v73 offset:53760
	ds_read_b64 v[58:59], v73 offset:53792
	ds_read_b64 v[60:61], v73 offset:62208
	ds_read_b64 v[62:63], v73 offset:62240
	ds_read_b64 v[64:65], v73 offset:36928
	ds_read_b64 v[66:67], v73 offset:36960
	s_waitcnt lgkmcnt(10)
	v_add_f32_e32 v36, v36, v37
	v_rcp_f32_e32 v142, v36
	s_nop 0
	v_fma_f32 v143, -v36, v142, 1.0
	v_fma_f32 v142, v143, v142, v142
	v_mov_b32_e32 v143, v142
	ds_read_b64 v[68:69], v73 offset:45376
	ds_read_b64 v[70:71], v73 offset:45408
	s_waitcnt lgkmcnt(10)
	v_mfma_f32_16x16x32_bf16 v[32:35], v[48:51], v[78:81], 0
	ds_read_b64 v[48:49], v73 offset:53824
	ds_read_b64 v[50:51], v73 offset:53856
	s_waitcnt lgkmcnt(10)
	v_mfma_f32_16x16x32_bf16 v[36:39], v[52:55], v[78:81], 0
	ds_read_b64 v[52:53], v73 offset:62272
	ds_read_b64 v[54:55], v73 offset:62304
	s_waitcnt lgkmcnt(10)
	v_mfma_f32_16x16x32_bf16 v[40:43], v[56:59], v[78:81], 0
	ds_read_b64 v[56:57], v73 offset:36992
	ds_read_b64 v[58:59], v73 offset:37024
	s_waitcnt lgkmcnt(10)
	v_mfma_f32_16x16x32_bf16 v[44:47], v[60:63], v[78:81], 0
	ds_read_b64 v[60:61], v73 offset:45440
	ds_read_b64 v[62:63], v73 offset:45472
	s_waitcnt lgkmcnt(10)
	v_mfma_f32_16x16x32_bf16 v[32:35], v[64:67], v[86:89], v[32:35]
	ds_read_b64 v[64:65], v73 offset:53888
	ds_read_b64 v[66:67], v73 offset:53920
	s_waitcnt lgkmcnt(10)
	v_mfma_f32_16x16x32_bf16 v[36:39], v[68:71], v[86:89], v[36:39]
	ds_read_b64 v[68:69], v73 offset:62336
	ds_read_b64 v[70:71], v73 offset:62368
	s_waitcnt lgkmcnt(10)
	v_mfma_f32_16x16x32_bf16 v[40:43], v[48:51], v[86:89], v[40:43]
	ds_read_b64 v[48:49], v73 offset:37056
	ds_read_b64 v[50:51], v73 offset:37088
	s_waitcnt lgkmcnt(10)
	v_mfma_f32_16x16x32_bf16 v[44:47], v[52:55], v[86:89], v[44:47]
	ds_read_b64 v[52:53], v73 offset:45504
	ds_read_b64 v[54:55], v73 offset:45536
	s_waitcnt lgkmcnt(10)
	v_mfma_f32_16x16x32_bf16 v[32:35], v[56:59], v[94:97], v[32:35]
	ds_read_b64 v[56:57], v73 offset:53952
	ds_read_b64 v[58:59], v73 offset:53984
	s_waitcnt lgkmcnt(10)
	v_mfma_f32_16x16x32_bf16 v[36:39], v[60:63], v[94:97], v[36:39]
	ds_read_b64 v[60:61], v73 offset:62400
	ds_read_b64 v[62:63], v73 offset:62432
	s_waitcnt lgkmcnt(10)
	v_mfma_f32_16x16x32_bf16 v[40:43], v[64:67], v[94:97], v[40:43]
	ds_read_b64 v[64:65], v73 offset:37120
	ds_read_b64 v[66:67], v73 offset:37152
	s_waitcnt lgkmcnt(10)
	v_mfma_f32_16x16x32_bf16 v[44:47], v[68:71], v[94:97], v[44:47]
	ds_read_b64 v[68:69], v73 offset:45568
	ds_read_b64 v[70:71], v73 offset:45600
	s_waitcnt lgkmcnt(10)
	v_mfma_f32_16x16x32_bf16 v[32:35], v[48:51], v[102:105], v[32:35]
	ds_read_b64 v[48:49], v73 offset:54016
	ds_read_b64 v[50:51], v73 offset:54048
	s_waitcnt lgkmcnt(10)
	v_mfma_f32_16x16x32_bf16 v[36:39], v[52:55], v[102:105], v[36:39]
	ds_read_b64 v[52:53], v73 offset:62464
	ds_read_b64 v[54:55], v73 offset:62496
	s_waitcnt lgkmcnt(10)
	v_mfma_f32_16x16x32_bf16 v[40:43], v[56:59], v[102:105], v[40:43]
	ds_read_b64 v[56:57], v73 offset:37184
	ds_read_b64 v[58:59], v73 offset:37216
	s_waitcnt lgkmcnt(10)
	v_mfma_f32_16x16x32_bf16 v[44:47], v[60:63], v[102:105], v[44:47]
	ds_read_b64 v[60:61], v73 offset:45632
	ds_read_b64 v[62:63], v73 offset:45664
	s_waitcnt lgkmcnt(10)
	v_mfma_f32_16x16x32_bf16 v[32:35], v[64:67], v[110:113], v[32:35]
	ds_read_b64 v[64:65], v73 offset:54080
	ds_read_b64 v[66:67], v73 offset:54112
	s_waitcnt lgkmcnt(10)
	v_mfma_f32_16x16x32_bf16 v[36:39], v[68:71], v[110:113], v[36:39]
	ds_read_b64 v[68:69], v73 offset:62528
	ds_read_b64 v[70:71], v73 offset:62560
	s_waitcnt lgkmcnt(10)
	v_mfma_f32_16x16x32_bf16 v[40:43], v[48:51], v[110:113], v[40:43]
	ds_read_b64 v[48:49], v73 offset:37248
	ds_read_b64 v[50:51], v73 offset:37280
	s_waitcnt lgkmcnt(10)
	v_mfma_f32_16x16x32_bf16 v[44:47], v[52:55], v[110:113], v[44:47]
	ds_read_b64 v[52:53], v73 offset:45696
	ds_read_b64 v[54:55], v73 offset:45728
	s_waitcnt lgkmcnt(10)
	v_mfma_f32_16x16x32_bf16 v[32:35], v[56:59], v[118:121], v[32:35]
	ds_read_b64 v[56:57], v73 offset:54144
	ds_read_b64 v[58:59], v73 offset:54176
	s_waitcnt lgkmcnt(10)
	v_mfma_f32_16x16x32_bf16 v[36:39], v[60:63], v[118:121], v[36:39]
	ds_read_b64 v[60:61], v73 offset:62592
	ds_read_b64 v[62:63], v73 offset:62624
	s_waitcnt lgkmcnt(10)
	v_mfma_f32_16x16x32_bf16 v[40:43], v[64:67], v[118:121], v[40:43]
	ds_read_b64 v[64:65], v73 offset:37312
	ds_read_b64 v[66:67], v73 offset:37344
	s_waitcnt lgkmcnt(10)
	v_mfma_f32_16x16x32_bf16 v[44:47], v[68:71], v[118:121], v[44:47]
	ds_read_b64 v[68:69], v73 offset:45760
	ds_read_b64 v[70:71], v73 offset:45792
	s_waitcnt lgkmcnt(10)
	v_mfma_f32_16x16x32_bf16 v[32:35], v[48:51], v[126:129], v[32:35]
	ds_read_b64 v[48:49], v73 offset:54208
	ds_read_b64 v[50:51], v73 offset:54240
	s_waitcnt lgkmcnt(10)
	v_mfma_f32_16x16x32_bf16 v[36:39], v[52:55], v[126:129], v[36:39]
	ds_read_b64 v[52:53], v73 offset:62656
	ds_read_b64 v[54:55], v73 offset:62688
	s_waitcnt lgkmcnt(10)
	v_mfma_f32_16x16x32_bf16 v[40:43], v[56:59], v[126:129], v[40:43]
	s_waitcnt lgkmcnt(8)
	v_mfma_f32_16x16x32_bf16 v[44:47], v[60:63], v[126:129], v[44:47]
	s_waitcnt lgkmcnt(6)
	v_mfma_f32_16x16x32_bf16 v[32:35], v[64:67], v[134:137], v[32:35]
	s_waitcnt lgkmcnt(4)
	v_mfma_f32_16x16x32_bf16 v[36:39], v[68:71], v[134:137], v[36:39]
	s_waitcnt lgkmcnt(2)
	v_mfma_f32_16x16x32_bf16 v[40:43], v[48:51], v[134:137], v[40:43]
	s_waitcnt lgkmcnt(0)
	v_mfma_f32_16x16x32_bf16 v[44:47], v[52:55], v[134:137], v[44:47]
	s_add_u32 s16, s12, 0x80000
	s_addc_u32 s17, s13, 0
	s_nop 7
	v_pk_mul_f32 v[32:33], v[32:33], v[142:143]
	v_pk_mul_f32 v[34:35], v[34:35], v[142:143]
	v_pk_mul_f32 v[36:37], v[36:37], v[142:143]
	v_pk_mul_f32 v[38:39], v[38:39], v[142:143]
	v_pk_mul_f32 v[40:41], v[40:41], v[142:143]
	v_pk_mul_f32 v[42:43], v[42:43], v[142:143]
	v_pk_mul_f32 v[44:45], v[44:45], v[142:143]
	v_pk_mul_f32 v[46:47], v[46:47], v[142:143]
	v_cvt_pk_bf16_f32 v32, v32, v33
	v_cvt_pk_bf16_f32 v33, v34, v35
	v_cvt_pk_bf16_f32 v36, v36, v37
	v_cvt_pk_bf16_f32 v37, v38, v39
	v_cvt_pk_bf16_f32 v40, v40, v41
	v_cvt_pk_bf16_f32 v41, v42, v43
	v_cvt_pk_bf16_f32 v44, v44, v45
	v_cvt_pk_bf16_f32 v45, v46, v47
	global_store_dwordx2 v74, v[32:33], s[16:17] offset:0
	global_store_dwordx2 v74, v[36:37], s[16:17] offset:32
	global_store_dwordx2 v74, v[40:41], s[16:17] offset:64
	global_store_dwordx2 v74, v[44:45], s[16:17] offset:96
	ds_read_b128 v[48:51], v72 offset:0
	ds_read_b128 v[52:55], v72 offset:64
	ds_read_b128 v[56:59], v72 offset:2304
	ds_read_b128 v[60:63], v72 offset:2368
	ds_read_b128 v[64:67], v72 offset:4608
	ds_read_b128 v[68:71], v72 offset:4672
	s_waitcnt lgkmcnt(5)
	v_mfma_f32_16x16x32_bf16 v[78:81], v[48:51], v[24:27], 0
	ds_read_b128 v[48:51], v72 offset:6912
	s_waitcnt lgkmcnt(5)
	v_mfma_f32_16x16x32_bf16 v[78:81], v[52:55], v[28:31], v[78:81]
	ds_read_b128 v[52:55], v72 offset:6976
	s_waitcnt lgkmcnt(5)
	v_mfma_f32_16x16x32_bf16 v[82:85], v[56:59], v[24:27], 0
	ds_read_b128 v[56:59], v72 offset:9216
	s_waitcnt lgkmcnt(5)
	v_mfma_f32_16x16x32_bf16 v[82:85], v[60:63], v[28:31], v[82:85]
	ds_read_b128 v[60:63], v72 offset:9280
	s_waitcnt lgkmcnt(5)
	v_mfma_f32_16x16x32_bf16 v[86:89], v[64:67], v[24:27], 0
	ds_read_b128 v[64:67], v72 offset:11520
	s_waitcnt lgkmcnt(5)
	v_mfma_f32_16x16x32_bf16 v[86:89], v[68:71], v[28:31], v[86:89]
	ds_read_b128 v[68:71], v72 offset:11584
	s_waitcnt lgkmcnt(5)
	v_mfma_f32_16x16x32_bf16 v[90:93], v[48:51], v[24:27], 0
	ds_read_b128 v[48:51], v72 offset:13824
	s_waitcnt lgkmcnt(5)
	v_mfma_f32_16x16x32_bf16 v[90:93], v[52:55], v[28:31], v[90:93]
	ds_read_b128 v[52:55], v72 offset:13888
	s_waitcnt lgkmcnt(5)
	v_mfma_f32_16x16x32_bf16 v[94:97], v[56:59], v[24:27], 0
	ds_read_b128 v[56:59], v72 offset:16128
	s_waitcnt lgkmcnt(5)
	v_mfma_f32_16x16x32_bf16 v[94:97], v[60:63], v[28:31], v[94:97]
	ds_read_b128 v[60:63], v72 offset:16192
	s_waitcnt lgkmcnt(5)
	v_mfma_f32_16x16x32_bf16 v[98:101], v[64:67], v[24:27], 0
	ds_read_b128 v[64:67], v72 offset:18432
	s_waitcnt lgkmcnt(5)
	v_mfma_f32_16x16x32_bf16 v[98:101], v[68:71], v[28:31], v[98:101]
	ds_read_b128 v[68:71], v72 offset:18496
	s_waitcnt lgkmcnt(5)
	v_mfma_f32_16x16x32_bf16 v[102:105], v[48:51], v[24:27], 0
	ds_read_b128 v[48:51], v72 offset:20736
	s_waitcnt lgkmcnt(5)
	v_mfma_f32_16x16x32_bf16 v[102:105], v[52:55], v[28:31], v[102:105]
	ds_read_b128 v[52:55], v72 offset:20800
	s_waitcnt lgkmcnt(5)
	v_mfma_f32_16x16x32_bf16 v[106:109], v[56:59], v[24:27], 0
	ds_read_b128 v[56:59], v72 offset:23040
	s_waitcnt lgkmcnt(5)
	v_mfma_f32_16x16x32_bf16 v[106:109], v[60:63], v[28:31], v[106:109]
	ds_read_b128 v[60:63], v72 offset:23104
	s_waitcnt lgkmcnt(5)
	v_mfma_f32_16x16x32_bf16 v[110:113], v[64:67], v[24:27], 0
	ds_read_b128 v[64:67], v72 offset:25344
	s_waitcnt lgkmcnt(5)
	v_mfma_f32_16x16x32_bf16 v[110:113], v[68:71], v[28:31], v[110:113]
	ds_read_b128 v[68:71], v72 offset:25408
	s_waitcnt lgkmcnt(5)
	v_mfma_f32_16x16x32_bf16 v[114:117], v[48:51], v[24:27], 0
	ds_read_b128 v[48:51], v72 offset:27648
	s_waitcnt lgkmcnt(5)
	v_mfma_f32_16x16x32_bf16 v[114:117], v[52:55], v[28:31], v[114:117]
	ds_read_b128 v[52:55], v72 offset:27712
	s_waitcnt lgkmcnt(5)
	v_mfma_f32_16x16x32_bf16 v[118:121], v[56:59], v[24:27], 0
	ds_read_b128 v[56:59], v72 offset:29952
	s_waitcnt lgkmcnt(5)
	v_mfma_f32_16x16x32_bf16 v[118:121], v[60:63], v[28:31], v[118:121]
	ds_read_b128 v[60:63], v72 offset:30016
	s_waitcnt lgkmcnt(5)
	v_mfma_f32_16x16x32_bf16 v[122:125], v[64:67], v[24:27], 0
	ds_read_b128 v[64:67], v72 offset:32256
	s_waitcnt lgkmcnt(5)
	v_mfma_f32_16x16x32_bf16 v[122:125], v[68:71], v[28:31], v[122:125]
	ds_read_b128 v[68:71], v72 offset:32320
	s_waitcnt lgkmcnt(5)
	v_mfma_f32_16x16x32_bf16 v[126:129], v[48:51], v[24:27], 0
	ds_read_b128 v[48:51], v72 offset:34560
	s_waitcnt lgkmcnt(5)
	v_mfma_f32_16x16x32_bf16 v[126:129], v[52:55], v[28:31], v[126:129]
	ds_read_b128 v[52:55], v72 offset:34624
	s_waitcnt lgkmcnt(5)
	v_mfma_f32_16x16x32_bf16 v[130:133], v[56:59], v[24:27], 0
	s_waitcnt lgkmcnt(4)
	v_mfma_f32_16x16x32_bf16 v[130:133], v[60:63], v[28:31], v[130:133]
	s_waitcnt lgkmcnt(3)
	v_mfma_f32_16x16x32_bf16 v[134:137], v[64:67], v[24:27], 0
	s_waitcnt lgkmcnt(2)
	v_mfma_f32_16x16x32_bf16 v[134:137], v[68:71], v[28:31], v[134:137]
	s_waitcnt lgkmcnt(1)
	v_mfma_f32_16x16x32_bf16 v[138:141], v[48:51], v[24:27], 0
	s_waitcnt lgkmcnt(0)
	v_mfma_f32_16x16x32_bf16 v[138:141], v[52:55], v[28:31], v[138:141]
	v_max3_f32 v36, v78, v79, v80
	v_max3_f32 v36, v36, v81, v82
	v_max3_f32 v36, v36, v83, v84
	v_max3_f32 v36, v36, v85, v86
	v_max3_f32 v36, v36, v87, v88
	v_max3_f32 v36, v36, v89, v90
	v_max3_f32 v36, v36, v91, v92
	v_max3_f32 v36, v36, v93, v94
	v_max3_f32 v36, v36, v95, v96
	v_max3_f32 v36, v36, v97, v98
	v_max3_f32 v36, v36, v99, v100
	v_max3_f32 v36, v36, v101, v102
	v_max3_f32 v36, v36, v103, v104
	v_max3_f32 v36, v36, v105, v106
	v_max3_f32 v36, v36, v107, v108
	v_max3_f32 v36, v36, v109, v110
	v_max3_f32 v36, v36, v111, v112
	v_max3_f32 v36, v36, v113, v114
	v_max3_f32 v36, v36, v115, v116
	v_max3_f32 v36, v36, v117, v118
	v_max3_f32 v36, v36, v119, v120
	v_max3_f32 v36, v36, v121, v122
	v_max3_f32 v36, v36, v123, v124
	v_max3_f32 v36, v36, v125, v126
	v_max3_f32 v36, v36, v127, v128
	v_max3_f32 v36, v36, v129, v130
	v_max3_f32 v36, v36, v131, v132
	v_max3_f32 v36, v36, v133, v134
	v_max3_f32 v36, v36, v135, v136
	v_max3_f32 v36, v36, v137, v138
	v_max3_f32 v36, v36, v139, v140
	v_max_f32_e32 v36, v36, v141
	ds_bpermute_b32 v37, v75, v36
	s_waitcnt lgkmcnt(0)
	v_max_f32_e32 v36, v36, v37
	ds_bpermute_b32 v37, v77, v36
	s_waitcnt lgkmcnt(0)
	v_max_f32_e32 v36, v36, v37
	v_mul_f32_e64 v34, v36, -v144
	v_mov_b32_e32 v32, 0
	v_mov_b32_e32 v33, 0
	v_mov_b32_e32 v35, v34
	v_pk_fma_f32 v[78:79], v[78:79], v[144:145], v[34:35]
	v_pk_fma_f32 v[80:81], v[80:81], v[144:145], v[34:35]
	v_exp_f32_e32 v78, v78
	v_exp_f32_e32 v79, v79
	v_exp_f32_e32 v80, v80
	v_exp_f32_e32 v81, v81
	v_pk_fma_f32 v[82:83], v[82:83], v[144:145], v[34:35]
	v_pk_fma_f32 v[84:85], v[84:85], v[144:145], v[34:35]
	v_exp_f32_e32 v82, v82
	v_exp_f32_e32 v83, v83
	v_exp_f32_e32 v84, v84
	v_exp_f32_e32 v85, v85
	v_pk_add_f32 v[32:33], v[32:33], v[78:79]
	v_pk_add_f32 v[32:33], v[32:33], v[80:81]
	v_pk_fma_f32 v[86:87], v[86:87], v[144:145], v[34:35]
	v_pk_fma_f32 v[88:89], v[88:89], v[144:145], v[34:35]
	v_exp_f32_e32 v86, v86
	v_exp_f32_e32 v87, v87
	v_exp_f32_e32 v88, v88
	v_exp_f32_e32 v89, v89
	v_pk_add_f32 v[32:33], v[32:33], v[82:83]
	v_pk_add_f32 v[32:33], v[32:33], v[84:85]
	v_pk_fma_f32 v[90:91], v[90:91], v[144:145], v[34:35]
	v_pk_fma_f32 v[92:93], v[92:93], v[144:145], v[34:35]
	v_exp_f32_e32 v90, v90
	v_exp_f32_e32 v91, v91
	v_exp_f32_e32 v92, v92
	v_exp_f32_e32 v93, v93
	v_pk_add_f32 v[32:33], v[32:33], v[86:87]
	v_pk_add_f32 v[32:33], v[32:33], v[88:89]
	v_pk_fma_f32 v[94:95], v[94:95], v[144:145], v[34:35]
	v_pk_fma_f32 v[96:97], v[96:97], v[144:145], v[34:35]
	v_exp_f32_e32 v94, v94
	v_exp_f32_e32 v95, v95
	v_exp_f32_e32 v96, v96
	v_exp_f32_e32 v97, v97
	v_pk_add_f32 v[32:33], v[32:33], v[90:91]
	v_pk_add_f32 v[32:33], v[32:33], v[92:93]
	v_pk_fma_f32 v[98:99], v[98:99], v[144:145], v[34:35]
	v_pk_fma_f32 v[100:101], v[100:101], v[144:145], v[34:35]
	v_exp_f32_e32 v98, v98
	v_exp_f32_e32 v99, v99
	v_exp_f32_e32 v100, v100
	v_exp_f32_e32 v101, v101
	v_pk_add_f32 v[32:33], v[32:33], v[94:95]
	v_pk_add_f32 v[32:33], v[32:33], v[96:97]
	v_pk_fma_f32 v[102:103], v[102:103], v[144:145], v[34:35]
	v_pk_fma_f32 v[104:105], v[104:105], v[144:145], v[34:35]
	v_exp_f32_e32 v102, v102
	v_exp_f32_e32 v103, v103
	v_exp_f32_e32 v104, v104
	v_exp_f32_e32 v105, v105
	v_pk_add_f32 v[32:33], v[32:33], v[98:99]
	v_pk_add_f32 v[32:33], v[32:33], v[100:101]
	v_pk_fma_f32 v[106:107], v[106:107], v[144:145], v[34:35]
	v_pk_fma_f32 v[108:109], v[108:109], v[144:145], v[34:35]
	v_exp_f32_e32 v106, v106
	v_exp_f32_e32 v107, v107
	v_exp_f32_e32 v108, v108
	v_exp_f32_e32 v109, v109
	v_pk_add_f32 v[32:33], v[32:33], v[102:103]
	v_pk_add_f32 v[32:33], v[32:33], v[104:105]
	v_pk_fma_f32 v[110:111], v[110:111], v[144:145], v[34:35]
	v_pk_fma_f32 v[112:113], v[112:113], v[144:145], v[34:35]
	v_exp_f32_e32 v110, v110
	v_exp_f32_e32 v111, v111
	v_exp_f32_e32 v112, v112
	v_exp_f32_e32 v113, v113
	v_pk_add_f32 v[32:33], v[32:33], v[106:107]
	v_pk_add_f32 v[32:33], v[32:33], v[108:109]
	v_pk_fma_f32 v[114:115], v[114:115], v[144:145], v[34:35]
	v_pk_fma_f32 v[116:117], v[116:117], v[144:145], v[34:35]
	v_exp_f32_e32 v114, v114
	v_exp_f32_e32 v115, v115
	v_exp_f32_e32 v116, v116
	v_exp_f32_e32 v117, v117
	v_pk_add_f32 v[32:33], v[32:33], v[110:111]
	v_pk_add_f32 v[32:33], v[32:33], v[112:113]
	v_pk_fma_f32 v[118:119], v[118:119], v[144:145], v[34:35]
	v_pk_fma_f32 v[120:121], v[120:121], v[144:145], v[34:35]
	v_exp_f32_e32 v118, v118
	v_exp_f32_e32 v119, v119
	v_exp_f32_e32 v120, v120
	v_exp_f32_e32 v121, v121
	v_pk_add_f32 v[32:33], v[32:33], v[114:115]
	v_pk_add_f32 v[32:33], v[32:33], v[116:117]
	v_pk_fma_f32 v[122:123], v[122:123], v[144:145], v[34:35]
	v_pk_fma_f32 v[124:125], v[124:125], v[144:145], v[34:35]
	v_exp_f32_e32 v122, v122
	v_exp_f32_e32 v123, v123
	v_exp_f32_e32 v124, v124
	v_exp_f32_e32 v125, v125
	v_pk_add_f32 v[32:33], v[32:33], v[118:119]
	v_pk_add_f32 v[32:33], v[32:33], v[120:121]
	v_pk_fma_f32 v[126:127], v[126:127], v[144:145], v[34:35]
	v_pk_fma_f32 v[128:129], v[128:129], v[144:145], v[34:35]
	v_exp_f32_e32 v126, v126
	v_exp_f32_e32 v127, v127
	v_exp_f32_e32 v128, v128
	v_exp_f32_e32 v129, v129
	v_pk_add_f32 v[32:33], v[32:33], v[122:123]
	v_pk_add_f32 v[32:33], v[32:33], v[124:125]
	v_pk_fma_f32 v[130:131], v[130:131], v[144:145], v[34:35]
	v_pk_fma_f32 v[132:133], v[132:133], v[144:145], v[34:35]
	v_exp_f32_e32 v130, v130
	v_exp_f32_e32 v131, v131
	v_exp_f32_e32 v132, v132
	v_exp_f32_e32 v133, v133
	v_pk_add_f32 v[32:33], v[32:33], v[126:127]
	v_pk_add_f32 v[32:33], v[32:33], v[128:129]
	v_pk_fma_f32 v[134:135], v[134:135], v[144:145], v[34:35]
	v_pk_fma_f32 v[136:137], v[136:137], v[144:145], v[34:35]
	v_exp_f32_e32 v134, v134
	v_exp_f32_e32 v135, v135
	v_exp_f32_e32 v136, v136
	v_exp_f32_e32 v137, v137
	v_pk_add_f32 v[32:33], v[32:33], v[130:131]
	v_pk_add_f32 v[32:33], v[32:33], v[132:133]
	v_pk_fma_f32 v[138:139], v[138:139], v[144:145], v[34:35]
	v_pk_fma_f32 v[140:141], v[140:141], v[144:145], v[34:35]
	v_exp_f32_e32 v138, v138
	v_exp_f32_e32 v139, v139
	v_exp_f32_e32 v140, v140
	v_exp_f32_e32 v141, v141
	v_pk_add_f32 v[32:33], v[32:33], v[134:135]
	v_pk_add_f32 v[32:33], v[32:33], v[136:137]
	s_nop 0
	v_pk_add_f32 v[32:33], v[32:33], v[138:139]
	v_pk_add_f32 v[32:33], v[32:33], v[140:141]
	v_add_f32_e32 v36, v32, v33
	ds_bpermute_b32 v37, v75, v36
	v_cvt_pk_bf16_f32 v78, v78, v79
	v_cvt_pk_bf16_f32 v79, v80, v81
	v_cvt_pk_bf16_f32 v80, v82, v83
	v_cvt_pk_bf16_f32 v81, v84, v85
	v_cvt_pk_bf16_f32 v86, v86, v87
	v_cvt_pk_bf16_f32 v87, v88, v89
	v_cvt_pk_bf16_f32 v88, v90, v91
	v_cvt_pk_bf16_f32 v89, v92, v93
	v_cvt_pk_bf16_f32 v94, v94, v95
	v_cvt_pk_bf16_f32 v95, v96, v97
	v_cvt_pk_bf16_f32 v96, v98, v99
	v_cvt_pk_bf16_f32 v97, v100, v101
	v_cvt_pk_bf16_f32 v102, v102, v103
	v_cvt_pk_bf16_f32 v103, v104, v105
	v_cvt_pk_bf16_f32 v104, v106, v107
	v_cvt_pk_bf16_f32 v105, v108, v109
	v_cvt_pk_bf16_f32 v110, v110, v111
	v_cvt_pk_bf16_f32 v111, v112, v113
	v_cvt_pk_bf16_f32 v112, v114, v115
	v_cvt_pk_bf16_f32 v113, v116, v117
	v_cvt_pk_bf16_f32 v118, v118, v119
	v_cvt_pk_bf16_f32 v119, v120, v121
	v_cvt_pk_bf16_f32 v120, v122, v123
	v_cvt_pk_bf16_f32 v121, v124, v125
	v_cvt_pk_bf16_f32 v126, v126, v127
	v_cvt_pk_bf16_f32 v127, v128, v129
	v_cvt_pk_bf16_f32 v128, v130, v131
	v_cvt_pk_bf16_f32 v129, v132, v133
	v_cvt_pk_bf16_f32 v134, v134, v135
	v_cvt_pk_bf16_f32 v135, v136, v137
	v_cvt_pk_bf16_f32 v136, v138, v139
	v_cvt_pk_bf16_f32 v137, v140, v141
	s_waitcnt lgkmcnt(0)
	v_add_f32_e32 v36, v36, v37
	ds_bpermute_b32 v37, v77, v36
	ds_read_b64 v[48:49], v73 offset:36864
	ds_read_b64 v[50:51], v73 offset:36896
	ds_read_b64 v[52:53], v73 offset:45312
	ds_read_b64 v[54:55], v73 offset:45344
	ds_read_b64 v[56:57], v73 offset:53760
	ds_read_b64 v[58:59], v73 offset:53792
	ds_read_b64 v[60:61], v73 offset:62208
	ds_read_b64 v[62:63], v73 offset:62240
	ds_read_b64 v[64:65], v73 offset:36928
	ds_read_b64 v[66:67], v73 offset:36960
	s_waitcnt lgkmcnt(10)
	v_add_f32_e32 v36, v36, v37
	v_rcp_f32_e32 v142, v36
	s_nop 0
	v_fma_f32 v143, -v36, v142, 1.0
	v_fma_f32 v142, v143, v142, v142
	v_mov_b32_e32 v143, v142
	ds_read_b64 v[68:69], v73 offset:45376
	ds_read_b64 v[70:71], v73 offset:45408
	s_waitcnt lgkmcnt(10)
	v_mfma_f32_16x16x32_bf16 v[32:35], v[48:51], v[78:81], 0
	ds_read_b64 v[48:49], v73 offset:53824
	ds_read_b64 v[50:51], v73 offset:53856
	s_waitcnt lgkmcnt(10)
	v_mfma_f32_16x16x32_bf16 v[36:39], v[52:55], v[78:81], 0
	ds_read_b64 v[52:53], v73 offset:62272
	ds_read_b64 v[54:55], v73 offset:62304
	s_waitcnt lgkmcnt(10)
	v_mfma_f32_16x16x32_bf16 v[40:43], v[56:59], v[78:81], 0
	ds_read_b64 v[56:57], v73 offset:36992
	ds_read_b64 v[58:59], v73 offset:37024
	s_waitcnt lgkmcnt(10)
	v_mfma_f32_16x16x32_bf16 v[44:47], v[60:63], v[78:81], 0
	ds_read_b64 v[60:61], v73 offset:45440
	ds_read_b64 v[62:63], v73 offset:45472
	s_waitcnt lgkmcnt(10)
	v_mfma_f32_16x16x32_bf16 v[32:35], v[64:67], v[86:89], v[32:35]
	ds_read_b64 v[64:65], v73 offset:53888
	ds_read_b64 v[66:67], v73 offset:53920
	s_waitcnt lgkmcnt(10)
	v_mfma_f32_16x16x32_bf16 v[36:39], v[68:71], v[86:89], v[36:39]
	ds_read_b64 v[68:69], v73 offset:62336
	ds_read_b64 v[70:71], v73 offset:62368
	s_waitcnt lgkmcnt(10)
	v_mfma_f32_16x16x32_bf16 v[40:43], v[48:51], v[86:89], v[40:43]
	ds_read_b64 v[48:49], v73 offset:37056
	ds_read_b64 v[50:51], v73 offset:37088
	s_waitcnt lgkmcnt(10)
	v_mfma_f32_16x16x32_bf16 v[44:47], v[52:55], v[86:89], v[44:47]
	ds_read_b64 v[52:53], v73 offset:45504
	ds_read_b64 v[54:55], v73 offset:45536
	s_waitcnt lgkmcnt(10)
	v_mfma_f32_16x16x32_bf16 v[32:35], v[56:59], v[94:97], v[32:35]
	ds_read_b64 v[56:57], v73 offset:53952
	ds_read_b64 v[58:59], v73 offset:53984
	s_waitcnt lgkmcnt(10)
	v_mfma_f32_16x16x32_bf16 v[36:39], v[60:63], v[94:97], v[36:39]
	ds_read_b64 v[60:61], v73 offset:62400
	ds_read_b64 v[62:63], v73 offset:62432
	s_waitcnt lgkmcnt(10)
	v_mfma_f32_16x16x32_bf16 v[40:43], v[64:67], v[94:97], v[40:43]
	ds_read_b64 v[64:65], v73 offset:37120
	ds_read_b64 v[66:67], v73 offset:37152
	s_waitcnt lgkmcnt(10)
	v_mfma_f32_16x16x32_bf16 v[44:47], v[68:71], v[94:97], v[44:47]
	ds_read_b64 v[68:69], v73 offset:45568
	ds_read_b64 v[70:71], v73 offset:45600
	s_waitcnt lgkmcnt(10)
	v_mfma_f32_16x16x32_bf16 v[32:35], v[48:51], v[102:105], v[32:35]
	ds_read_b64 v[48:49], v73 offset:54016
	ds_read_b64 v[50:51], v73 offset:54048
	s_waitcnt lgkmcnt(10)
	v_mfma_f32_16x16x32_bf16 v[36:39], v[52:55], v[102:105], v[36:39]
	ds_read_b64 v[52:53], v73 offset:62464
	ds_read_b64 v[54:55], v73 offset:62496
	s_waitcnt lgkmcnt(10)
	v_mfma_f32_16x16x32_bf16 v[40:43], v[56:59], v[102:105], v[40:43]
	ds_read_b64 v[56:57], v73 offset:37184
	ds_read_b64 v[58:59], v73 offset:37216
	s_waitcnt lgkmcnt(10)
	v_mfma_f32_16x16x32_bf16 v[44:47], v[60:63], v[102:105], v[44:47]
	ds_read_b64 v[60:61], v73 offset:45632
	ds_read_b64 v[62:63], v73 offset:45664
	s_waitcnt lgkmcnt(10)
	v_mfma_f32_16x16x32_bf16 v[32:35], v[64:67], v[110:113], v[32:35]
	ds_read_b64 v[64:65], v73 offset:54080
	ds_read_b64 v[66:67], v73 offset:54112
	s_waitcnt lgkmcnt(10)
	v_mfma_f32_16x16x32_bf16 v[36:39], v[68:71], v[110:113], v[36:39]
	ds_read_b64 v[68:69], v73 offset:62528
	ds_read_b64 v[70:71], v73 offset:62560
	s_waitcnt lgkmcnt(10)
	v_mfma_f32_16x16x32_bf16 v[40:43], v[48:51], v[110:113], v[40:43]
	ds_read_b64 v[48:49], v73 offset:37248
	ds_read_b64 v[50:51], v73 offset:37280
	s_waitcnt lgkmcnt(10)
	v_mfma_f32_16x16x32_bf16 v[44:47], v[52:55], v[110:113], v[44:47]
	ds_read_b64 v[52:53], v73 offset:45696
	ds_read_b64 v[54:55], v73 offset:45728
	s_waitcnt lgkmcnt(10)
	v_mfma_f32_16x16x32_bf16 v[32:35], v[56:59], v[118:121], v[32:35]
	ds_read_b64 v[56:57], v73 offset:54144
	ds_read_b64 v[58:59], v73 offset:54176
	s_waitcnt lgkmcnt(10)
	v_mfma_f32_16x16x32_bf16 v[36:39], v[60:63], v[118:121], v[36:39]
	ds_read_b64 v[60:61], v73 offset:62592
	ds_read_b64 v[62:63], v73 offset:62624
	s_waitcnt lgkmcnt(10)
	v_mfma_f32_16x16x32_bf16 v[40:43], v[64:67], v[118:121], v[40:43]
	ds_read_b64 v[64:65], v73 offset:37312
	ds_read_b64 v[66:67], v73 offset:37344
	s_waitcnt lgkmcnt(10)
	v_mfma_f32_16x16x32_bf16 v[44:47], v[68:71], v[118:121], v[44:47]
	ds_read_b64 v[68:69], v73 offset:45760
	ds_read_b64 v[70:71], v73 offset:45792
	s_waitcnt lgkmcnt(10)
	v_mfma_f32_16x16x32_bf16 v[32:35], v[48:51], v[126:129], v[32:35]
	ds_read_b64 v[48:49], v73 offset:54208
	ds_read_b64 v[50:51], v73 offset:54240
	s_waitcnt lgkmcnt(10)
	v_mfma_f32_16x16x32_bf16 v[36:39], v[52:55], v[126:129], v[36:39]
	ds_read_b64 v[52:53], v73 offset:62656
	ds_read_b64 v[54:55], v73 offset:62688
	s_waitcnt lgkmcnt(10)
	v_mfma_f32_16x16x32_bf16 v[40:43], v[56:59], v[126:129], v[40:43]
	s_waitcnt lgkmcnt(8)
	v_mfma_f32_16x16x32_bf16 v[44:47], v[60:63], v[126:129], v[44:47]
	s_waitcnt lgkmcnt(6)
	v_mfma_f32_16x16x32_bf16 v[32:35], v[64:67], v[134:137], v[32:35]
	s_waitcnt lgkmcnt(4)
	v_mfma_f32_16x16x32_bf16 v[36:39], v[68:71], v[134:137], v[36:39]
	s_waitcnt lgkmcnt(2)
	v_mfma_f32_16x16x32_bf16 v[40:43], v[48:51], v[134:137], v[40:43]
	s_waitcnt lgkmcnt(0)
	v_mfma_f32_16x16x32_bf16 v[44:47], v[52:55], v[134:137], v[44:47]
	s_add_u32 s16, s12, 0x88000
	s_addc_u32 s17, s13, 0
	s_nop 7
	v_pk_mul_f32 v[32:33], v[32:33], v[142:143]
	v_pk_mul_f32 v[34:35], v[34:35], v[142:143]
	v_pk_mul_f32 v[36:37], v[36:37], v[142:143]
	v_pk_mul_f32 v[38:39], v[38:39], v[142:143]
	v_pk_mul_f32 v[40:41], v[40:41], v[142:143]
	v_pk_mul_f32 v[42:43], v[42:43], v[142:143]
	v_pk_mul_f32 v[44:45], v[44:45], v[142:143]
	v_pk_mul_f32 v[46:47], v[46:47], v[142:143]
	v_cvt_pk_bf16_f32 v32, v32, v33
	v_cvt_pk_bf16_f32 v33, v34, v35
	v_cvt_pk_bf16_f32 v36, v36, v37
	v_cvt_pk_bf16_f32 v37, v38, v39
	v_cvt_pk_bf16_f32 v40, v40, v41
	v_cvt_pk_bf16_f32 v41, v42, v43
	v_cvt_pk_bf16_f32 v44, v44, v45
	v_cvt_pk_bf16_f32 v45, v46, v47
	global_store_dwordx2 v74, v[32:33], s[16:17] offset:0
	global_store_dwordx2 v74, v[36:37], s[16:17] offset:32
	global_store_dwordx2 v74, v[40:41], s[16:17] offset:64
	global_store_dwordx2 v74, v[44:45], s[16:17] offset:96
	s_barrier
	s_branch .LBB0_270
